# rwkv_out epilogue param/BON loads hoisted into one batch; ret_out gate loads paired; SWA next-head Q prefetch
# speedup vs baseline: 1.0286x; 1.0004x over previous
; __device__ __forceinline__ void swa_phase(const bf16* QKV, bf16* MIX, const float* sinks, unsigned char* lds) {
;     ...
;         const int b = u >> 9, kvh = (u >> 7) & 3, n = u & 127; const size_t rowbase = (size_t)b * SEQ + n * 128;
;         __syncthreads();
; #pragma unroll
;         for (int it = 0; it < 4; ++it) { const int ci = tid + it * NTHR, kj = ci >> 3, c8 = (ci & 7) * 8; *(u32x4*)(Ks + kj * 72 + c8) = pk_[it]; *(u32x4*)(Vs + kj * 72 + c8) = pv_[it]; }
;         __syncthreads();
;         { const int un = u + (int)gridDim.x; if (un < 1024) SWA_FETCH(un); }
;         for (int g = 0; g < 4; ++g) {
;             const int hq = kvh * 4 + g;
;             bf16x8 qf[2];
; #pragma unroll
;             for (int ks = 0; ks < 2; ++ks) qf[ks] = *(const bf16x8*)(QKV + (rowbase + 16 * wave + r16) * QKVW + hq * 64 + 32 * ks + q4 * 8);
;             f32x4 acc[16];
;             const float sink = sinks[hq];
;             float mx[4] = {-INFINITY, -INFINITY, -INFINITY, -INFINITY};
; #pragma unroll
;             for (int kt = 0; kt < 16; ++kt) {
;                 if (kt >= wave && kt <= wave + 8) {
;                     acc[kt] = (f32x4){0.f, 0.f, 0.f, 0.f};
; #pragma unroll
;                     for (int ks = 0; ks < 2; ++ks) acc[kt] = __builtin_amdgcn_mfma_f32_16x16x32_bf16(qf[ks], *(const bf16x8*)(Ks + (16 * kt + r16) * 72 + 32 * ks + q4 * 8), acc[kt], 0, 0, 0);
; #pragma unroll
;                     for (int jj = 0; jj < 4; ++jj) { const int qi = 16 * wave + q4 * 4 + jj, kj = 16 * kt + r16, rel = qi + 128 - kj;
;                         const bool valid = (rel >= 0) && (rel < 128) && ((n > 0) || (kj >= 128));
.LBB0_282:
	v_writelane_b32 v236, s19, 19
	v_writelane_b32 v236, s24, 20
	s_lshr_b32 s4, s14, 3
	s_and_b32 s4, s4, 48
	v_writelane_b32 v236, s25, 21
	v_writelane_b32 v236, s26, 22
	v_writelane_b32 v236, s27, 23
	v_readlane_b32 s58, v237, 0
	v_readlane_b32 s5, v236, 14
	s_add_u32 s82, s5, s4
	v_readlane_b32 s4, v236, 15
	s_addc_u32 s83, s4, 0
	s_and_b32 s4, s18, 0x7f
	s_lshl_b32 s6, s4, 7
	s_lshl_b32 s4, s14, 2
	s_and_b32 s7, s4, 0x600
	s_ashr_i32 s4, s14, 9
	s_ashr_i32 s5, s4, 31
	s_and_b32 s10, s14, 0x7f
	s_lshl_b64 s[4:5], s[4:5], 14
	s_cmp_eq_u32 s10, 0
	v_readlane_b32 s10, v238, 14
	s_cselect_b64 s[74:75], -1, 0
	v_readlane_b32 s11, v238, 15
	s_or_b64 s[10:11], s[10:11], s[74:75]
	v_writelane_b32 v239, s10, 62
	s_or_b32 s4, s4, s6
	v_lshl_add_u64 v[2:3], s[4:5], 0, v[74:75]
	v_writelane_b32 v239, s11, 63
	v_readlane_b32 s10, v238, 16
	v_readlane_b32 s11, v238, 17
	s_or_b64 s[10:11], s[10:11], s[74:75]
	v_writelane_b32 v238, s10, 0
	v_lshl_add_u64 v[36:37], s[4:5], 0, v[72:73]
	v_lshl_add_u64 v[38:39], s[4:5], 0, v[56:57]
	v_writelane_b32 v238, s11, 1
	v_writelane_b32 v236, s18, 16
	v_readlane_b32 s10, v238, 18
	v_readlane_b32 s11, v238, 19
	s_or_b64 s[10:11], s[10:11], s[74:75]
	v_writelane_b32 v238, s10, 2
	v_lshlrev_b64 v[2:3], 11, v[2:3]
	v_lshlrev_b64 v[36:37], 11, v[36:37]
	v_writelane_b32 v238, s11, 3
	v_mov_b32_e32 v0, s7
	v_readlane_b32 s10, v238, 20
	v_readlane_b32 s11, v238, 21
	s_or_b64 s[10:11], s[10:11], s[74:75]
	v_writelane_b32 v238, s10, 4
	v_or_b32_e32 v2, s7, v2
	v_or_b32_e32 v36, s7, v36
	v_writelane_b32 v238, s11, 5
	v_readlane_b32 s60, v237, 2
	v_readlane_b32 s10, v238, 22
	v_readlane_b32 s11, v238, 23
	s_or_b64 s[10:11], s[10:11], s[74:75]
	v_writelane_b32 v239, s10, 44
	v_readlane_b32 s4, v238, 34
	v_readlane_b32 s5, v238, 35
	v_writelane_b32 v239, s11, 45
	v_readlane_b32 s10, v238, 24
	v_readlane_b32 s11, v238, 25
	s_or_b64 s[10:11], s[10:11], s[74:75]
	v_writelane_b32 v239, s10, 46
	s_or_b64 s[4:5], s[4:5], s[74:75]
	v_readlane_b32 s6, v238, 44
	v_writelane_b32 v239, s11, 47
	v_readlane_b32 s10, v238, 26
	v_readlane_b32 s11, v238, 27
	s_or_b64 s[10:11], s[10:11], s[74:75]
	v_writelane_b32 v239, s10, 50
	v_readlane_b32 s14, v238, 48
	v_readlane_b32 s16, v238, 50
	v_writelane_b32 v239, s11, 51
	v_readlane_b32 s10, v238, 28
	v_readlane_b32 s11, v238, 29
	s_or_b64 s[10:11], s[10:11], s[74:75]
	v_writelane_b32 v239, s10, 48
	v_readlane_b32 s18, v238, 52
	v_readlane_b32 s24, v238, 54
	v_writelane_b32 v239, s11, 49
	v_readlane_b32 s10, v238, 30
	v_readlane_b32 s11, v238, 31
	s_or_b64 s[10:11], s[10:11], s[74:75]
	v_writelane_b32 v239, s10, 54
	v_readlane_b32 s26, v238, 56
	v_readlane_b32 s28, v238, 58
	v_writelane_b32 v239, s11, 55
	v_readlane_b32 s10, v238, 32
	v_readlane_b32 s11, v238, 33
	s_or_b64 s[10:11], s[10:11], s[74:75]
	v_writelane_b32 v239, s10, 60
	v_readlane_b32 s30, v238, 60
	v_readlane_b32 s54, v238, 62
	v_writelane_b32 v239, s11, 61
	v_writelane_b32 v239, s4, 56
	v_readlane_b32 s10, v238, 46
	v_readlane_b32 s62, v237, 4
	v_writelane_b32 v239, s5, 57
	v_readlane_b32 s4, v238, 36
	v_readlane_b32 s5, v238, 37
	s_or_b64 s[4:5], s[4:5], s[74:75]
	v_writelane_b32 v236, s4, 24
	v_readlane_b32 s68, v237, 6
	v_readlane_b32 s70, v237, 8
	v_writelane_b32 v236, s5, 25
	v_readlane_b32 s4, v238, 38
	v_readlane_b32 s5, v238, 39
	s_or_b64 s[4:5], s[4:5], s[74:75]
	v_writelane_b32 v236, s4, 26
	v_readlane_b32 s72, v237, 10
	v_readlane_b32 s84, v237, 12
	v_writelane_b32 v236, s5, 27
	v_readlane_b32 s4, v238, 40
	v_readlane_b32 s5, v238, 41
	s_or_b64 s[94:95], s[4:5], s[74:75]
	v_readlane_b32 s4, v238, 42
	v_readlane_b32 s5, v238, 43
	v_readlane_b32 s7, v238, 45
	v_readlane_b32 s11, v238, 47
	v_readlane_b32 s15, v238, 49
	v_readlane_b32 s17, v238, 51
	v_readlane_b32 s19, v238, 53
	v_readlane_b32 s25, v238, 55
	v_readlane_b32 s27, v238, 57
	v_readlane_b32 s29, v238, 59
	v_readlane_b32 s31, v238, 61
	v_readlane_b32 s55, v238, 63
	v_readlane_b32 s59, v237, 1
	v_readlane_b32 s61, v237, 3
	v_readlane_b32 s63, v237, 5
	v_readlane_b32 s69, v237, 7
	v_readlane_b32 s71, v237, 9
	v_readlane_b32 s73, v237, 11
	v_readlane_b32 s85, v237, 13
	s_movk_i32 s88, 0xc00
	s_or_b64 s[4:5], s[4:5], s[74:75]
	s_or_b64 s[6:7], s[6:7], s[74:75]
	s_or_b64 s[10:11], s[10:11], s[74:75]
	s_or_b64 s[14:15], s[14:15], s[74:75]
	s_or_b64 s[16:17], s[16:17], s[74:75]
	s_or_b64 s[18:19], s[18:19], s[74:75]
	s_or_b64 s[24:25], s[24:25], s[74:75]
	s_or_b64 s[26:27], s[26:27], s[74:75]
	s_or_b64 s[28:29], s[28:29], s[74:75]
	s_or_b64 s[30:31], s[30:31], s[74:75]
	s_or_b64 s[54:55], s[54:55], s[74:75]
	s_or_b64 s[58:59], s[58:59], s[74:75]
	s_or_b64 s[60:61], s[60:61], s[74:75]
	s_or_b64 s[62:63], s[62:63], s[74:75]
	s_or_b64 s[68:69], s[68:69], s[74:75]
	s_or_b64 s[70:71], s[70:71], s[74:75]
	s_or_b64 s[72:73], s[72:73], s[74:75]
	s_or_b64 s[74:75], s[84:85], s[74:75]
	v_lshl_add_u64 v[80:81], v[76:77], 0, v[2:3]
	v_mad_u64_u32 v[2:3], s[84:85], v38, s88, v[0:1]
	v_mov_b32_e32 v0, v3
	v_lshl_add_u64 v[82:83], v[76:77], 0, v[36:37]
	v_mad_u64_u32 v[36:37], s[84:85], v39, s88, v[0:1]
	v_mov_b32_e32 v3, v36
	v_lshl_add_u64 v[84:85], v[78:79], 0, v[2:3]
	s_mov_b64 s[84:85], 0
	v_add_co_u32_e32 v190, vcc, 0x6100000, v84
	s_nop 1
	v_addc_co_u32_e32 v191, vcc, 0, v85, vcc
	global_load_dwordx4 v[180:183], v[190:191], off
	global_load_dwordx4 v[184:187], v[190:191], off offset:64
	global_load_dword v188, v1, s[82:83]
	s_waitcnt vmcnt(0)
	s_branch .Lswa_q_ready

; __device__ __forceinline__ void swa_phase(const bf16* QKV, bf16* MIX, const float* sinks, unsigned char* lds) {
;     ...
;         for (int g = 0; g < 4; ++g) {
;             const int hq = kvh * 4 + g;
;             bf16x8 qf[2];
; #pragma unroll
;             for (int ks = 0; ks < 2; ++ks) qf[ks] = *(const bf16x8*)(QKV + (rowbase + 16 * wave + r16) * QKVW + hq * 64 + 32 * ks + q4 * 8);
;             f32x4 acc[16];
;             const float sink = sinks[hq];
;             float mx[4] = {-INFINITY, -INFINITY, -INFINITY, -INFINITY};
; #pragma unroll
;             for (int kt = 0; kt < 16; ++kt) {
;                 if (kt >= wave && kt <= wave + 8) {
;                     acc[kt] = (f32x4){0.f, 0.f, 0.f, 0.f};
; #pragma unroll
;                     for (int ks = 0; ks < 2; ++ks) acc[kt] = __builtin_amdgcn_mfma_f32_16x16x32_bf16(qf[ks], *(const bf16x8*)(Ks + (16 * kt + r16) * 72 + 32 * ks + q4 * 8), acc[kt], 0, 0, 0);
; #pragma unroll
;                     for (int jj = 0; jj < 4; ++jj) { const int qi = 16 * wave + q4 * 4 + jj, kj = 16 * kt + r16, rel = qi + 128 - kj;
;                         const bool valid = (rel >= 0) && (rel < 128) && ((n > 0) || (kj >= 128));
;                         const float sv = valid ? acc[kt][jj] * 0.125f : -INFINITY; acc[kt][jj] = sv; mx[jj] = fmaxf(mx[jj], sv); }
.LBB0_284:
	s_waitcnt vmcnt(2)
.Lswa_q_ready:
	v_mov_b32_e32 v0, 0xff800000
	v_mov_b64_e32 v[40:41], v[180:181]
	v_mov_b64_e32 v[42:43], v[182:183]
	v_mov_b64_e32 v[36:37], v[184:185]
	v_mov_b64_e32 v[38:39], v[186:187]
	v_mov_b32_e32 v139, v188
	s_cmpk_eq_i32 s84, 0x180
	s_cbranch_scc1 .Lswa_q_last
	v_lshl_add_u64 v[2:3], v[190:191], 0, s[84:85]
	global_load_dwordx4 v[180:183], v[2:3], off offset:128
	global_load_dwordx4 v[184:187], v[2:3], off offset:192
	global_load_dword v188, v1, s[82:83] offset:4
.Lswa_q_last:
	v_mov_b32_e32 v2, 0xff800000
	v_mov_b32_e32 v3, 0xff800000
	v_mov_b32_e32 v108, 0xff800000
	v_mov_b32_e32 v109, 0xff800000
	v_mov_b32_e32 v45, 0xff800000
	v_mov_b32_e32 v47, 0xff800000
	v_mov_b32_e32 v44, 0xff800000
	v_mov_b32_e32 v46, 0xff800000
	s_and_saveexec_b64 vcc, s[46:47]
	s_cbranch_execz .LBB0_286
	ds_read_b128 v[44:47], v138
	ds_read_b128 v[48:51], v138 offset:64
	v_readlane_b32 s88, v239, 62
	v_readlane_b32 s89, v239, 63
	s_waitcnt lgkmcnt(1)
	v_mfma_f32_16x16x32_bf16 v[44:47], v[40:43], v[44:47], 0
	s_waitcnt lgkmcnt(0)
	v_mfma_f32_16x16x32_bf16 v[44:47], v[36:39], v[48:51], v[44:47]
	s_nop 7
	v_mul_f32_e32 v0, 0x3e000000, v44
	v_mul_f32_e32 v3, 0x3e000000, v45
	v_cndmask_b32_e64 v45, v0, v168, s[88:89]
	v_readlane_b32 s88, v238, 0
	v_readlane_b32 s89, v238, 1
	v_mul_f32_e32 v44, 0x3e000000, v46
	v_mul_f32_e32 v46, 0x3e000000, v47
	v_cndmask_b32_e64 v47, v3, v168, s[88:89]
	v_readlane_b32 s88, v238, 2
	v_readlane_b32 s89, v238, 3
	v_max_f32_e32 v109, 0xff800000, v45
	v_max_f32_e32 v108, 0xff800000, v47
	v_cndmask_b32_e64 v44, v44, v168, s[88:89]
	v_readlane_b32 s88, v238, 4
	v_readlane_b32 s89, v238, 5
	v_max_f32_e32 v3, 0xff800000, v44
	s_nop 0
	v_cndmask_b32_e64 v46, v46, v168, s[88:89]
	v_max_f32_e32 v0, 0xff800000, v46
.LBB0_286:
	s_or_b64 exec, exec, vcc
	v_mov_b32_e32 v49, 0xff800000
	v_mov_b32_e32 v48, 0xff800000
	v_mov_b32_e32 v51, 0xff800000
	s_and_saveexec_b64 vcc, s[56:57]
	s_cbranch_execz .LBB0_288
	ds_read_b128 v[48:51], v138 offset:2304
	ds_read_b128 v[86:89], v138 offset:2368
	v_readlane_b32 s88, v239, 44
	v_readlane_b32 s89, v239, 45
	v_max_f32_e32 v90, v109, v109
	s_waitcnt lgkmcnt(1)
	v_mfma_f32_16x16x32_bf16 v[48:51], v[40:43], v[48:51], 0
	v_max_f32_e32 v91, v108, v108
	v_max_f32_e32 v3, v3, v3
	v_max_f32_e32 v0, v0, v0
	s_waitcnt lgkmcnt(0)
	v_mfma_f32_16x16x32_bf16 v[48:51], v[36:39], v[86:89], v[48:51]
	s_nop 7
	v_mul_f32_e32 v2, 0x3e000000, v48
	v_cndmask_b32_e64 v2, v2, v168, s[88:89]
	v_readlane_b32 s88, v239, 46
	v_mul_f32_e32 v48, 0x3e000000, v49
	v_readlane_b32 s89, v239, 47
	v_mul_f32_e32 v50, 0x3e000000, v50
	v_max_f32_e32 v109, v90, v2
	v_cndmask_b32_e64 v49, v48, v168, s[88:89]
	v_readlane_b32 s88, v239, 50
	v_readlane_b32 s89, v239, 51
	v_max_f32_e32 v108, v91, v49
	s_nop 0
	v_cndmask_b32_e64 v48, v50, v168, s[88:89]
	v_readlane_b32 s88, v239, 48
	v_mul_f32_e32 v50, 0x3e000000, v51
	v_readlane_b32 s89, v239, 49
	v_max_f32_e32 v3, v3, v48
	s_nop 0
	v_cndmask_b32_e64 v51, v50, v168, s[88:89]
	v_max_f32_e32 v0, v0, v51
.LBB0_288:
	s_or_b64 exec, exec, vcc
	v_mov_b32_e32 v50, 0xff800000
	v_mov_b32_e32 v88, 0xff800000
	v_mov_b32_e32 v89, 0xff800000
	v_mov_b32_e32 v87, 0xff800000
	v_mov_b32_e32 v90, 0xff800000
	s_and_saveexec_b64 vcc, s[66:67]
	s_cbranch_execz .LBB0_290
	ds_read_b128 v[86:89], v138 offset:4608
	ds_read_b128 v[90:93], v138 offset:4672
	v_readlane_b32 s88, v239, 54
	v_readlane_b32 s89, v239, 55
	v_max_f32_e32 v94, v109, v109
	s_waitcnt lgkmcnt(1)
	v_mfma_f32_16x16x32_bf16 v[86:89], v[40:43], v[86:89], 0
	v_max_f32_e32 v95, v108, v108
	v_max_f32_e32 v3, v3, v3
	v_max_f32_e32 v0, v0, v0
	s_waitcnt lgkmcnt(0)
	v_mfma_f32_16x16x32_bf16 v[88:91], v[36:39], v[90:93], v[86:89]
	s_nop 7
	v_mul_f32_e32 v86, 0x3e000000, v88
	v_cndmask_b32_e64 v88, v86, v168, s[88:89]
	v_readlane_b32 s88, v239, 60
	v_mul_f32_e32 v87, 0x3e000000, v89
	v_readlane_b32 s89, v239, 61
	v_mul_f32_e32 v90, 0x3e000000, v90
	v_mul_f32_e32 v86, 0x3e000000, v91
	v_cndmask_b32_e64 v89, v87, v168, s[88:89]
	v_readlane_b32 s88, v239, 56
	v_readlane_b32 s89, v239, 57
	v_max_f32_e32 v109, v94, v88
	v_max_f32_e32 v108, v95, v89
	v_cndmask_b32_e64 v87, v90, v168, s[88:89]
	v_readlane_b32 s88, v236, 24
	v_readlane_b32 s89, v236, 25
	v_max_f32_e32 v3, v3, v87
	s_nop 0
	v_cndmask_b32_e64 v90, v86, v168, s[88:89]
	v_max_f32_e32 v0, v0, v90
.LBB0_290:
	s_or_b64 exec, exec, vcc
	v_mov_b32_e32 v93, 0xff800000
	v_mov_b32_e32 v91, 0xff800000
	v_mov_b32_e32 v92, 0xff800000
	s_and_saveexec_b64 vcc, s[76:77]
	s_cbranch_execz .LBB0_292
	ds_read_b128 v[92:95], v138 offset:6912
	ds_read_b128 v[96:99], v138 offset:6976
	v_readlane_b32 s88, v236, 26
	v_readlane_b32 s89, v236, 27
	v_max_f32_e32 v86, v109, v109
	s_waitcnt lgkmcnt(1)
	v_mfma_f32_16x16x32_bf16 v[92:95], v[40:43], v[92:95], 0
	v_max_f32_e32 v100, v108, v108
	v_max_f32_e32 v3, v3, v3
	v_max_f32_e32 v0, v0, v0
	s_waitcnt lgkmcnt(0)
	v_mfma_f32_16x16x32_bf16 v[92:95], v[36:39], v[96:99], v[92:95]
	s_nop 7
	v_mul_f32_e32 v50, 0x3e000000, v92
	v_cndmask_b32_e64 v50, v50, v168, s[88:89]
	v_mul_f32_e32 v91, 0x3e000000, v93
	v_mul_f32_e32 v92, 0x3e000000, v94
	v_max_f32_e32 v109, v86, v50
	v_mul_f32_e32 v86, 0x3e000000, v95
	v_cndmask_b32_e64 v93, v91, v168, s[94:95]
	v_cndmask_b32_e64 v91, v92, v168, s[4:5]
	v_cndmask_b32_e64 v92, v86, v168, s[6:7]
	v_max_f32_e32 v108, v100, v93
	v_max_f32_e32 v3, v3, v91
	v_max_f32_e32 v0, v0, v92
; __device__ __forceinline__ void swa_phase(const bf16* QKV, bf16* MIX, const float* sinks, unsigned char* lds) {
;     ...
;             for (int kt = 0; kt < 16; ++kt) {
;                 if (kt >= wave && kt <= wave + 8) {
;                     acc[kt] = (f32x4){0.f, 0.f, 0.f, 0.f};
; #pragma unroll
;                     for (int ks = 0; ks < 2; ++ks) acc[kt] = __builtin_amdgcn_mfma_f32_16x16x32_bf16(qf[ks], *(const bf16x8*)(Ks + (16 * kt + r16) * 72 + 32 * ks + q4 * 8), acc[kt], 0, 0, 0);
; #pragma unroll
;                     for (int jj = 0; jj < 4; ++jj) { const int qi = 16 * wave + q4 * 4 + jj, kj = 16 * kt + r16, rel = qi + 128 - kj;
;                         const bool valid = (rel >= 0) && (rel < 128) && ((n > 0) || (kj >= 128));
;                         const float sv = valid ? acc[kt][jj] * 0.125f : -INFINITY; acc[kt][jj] = sv; mx[jj] = fmaxf(mx[jj], sv); }
;                 } else acc[kt] = (f32x4){-INFINITY, -INFINITY, -INFINITY, -INFINITY};
;             }
.LBB0_292:
	s_or_b64 exec, exec, vcc
	v_mov_b32_e32 v86, 0xff800000
	v_mov_b32_e32 v98, 0xff800000
	v_mov_b32_e32 v97, 0xff800000
	v_mov_b32_e32 v95, 0xff800000
	v_mov_b32_e32 v96, 0xff800000
	s_and_saveexec_b64 vcc, s[86:87]
	s_cbranch_execz .LBB0_294
	ds_read_b128 v[94:97], v138 offset:9216
	ds_read_b128 v[98:101], v138 offset:9280
	v_max_f32_e32 v102, v109, v109
	v_max_f32_e32 v103, v108, v108
	v_max_f32_e32 v3, v3, v3
	s_waitcnt lgkmcnt(1)
	v_mfma_f32_16x16x32_bf16 v[94:97], v[40:43], v[94:97], 0
	v_max_f32_e32 v0, v0, v0
	s_waitcnt lgkmcnt(0)
	v_mfma_f32_16x16x32_bf16 v[96:99], v[36:39], v[98:101], v[94:97]
	s_nop 7
	v_mul_f32_e32 v94, 0x3e000000, v96
	v_mul_f32_e32 v95, 0x3e000000, v97
	v_mul_f32_e32 v96, 0x3e000000, v98
	v_cndmask_b32_e64 v98, v94, v168, s[10:11]
	v_mul_f32_e32 v94, 0x3e000000, v99
	v_cndmask_b32_e64 v97, v95, v168, s[14:15]
	v_cndmask_b32_e64 v95, v96, v168, s[16:17]
	v_cndmask_b32_e64 v96, v94, v168, s[18:19]
	v_max_f32_e32 v109, v102, v98
	v_max_f32_e32 v108, v103, v97
	v_max_f32_e32 v3, v3, v95
	v_max_f32_e32 v0, v0, v96
.LBB0_294:
	s_or_b64 exec, exec, vcc
	v_mov_b32_e32 v101, 0xff800000
	v_mov_b32_e32 v99, 0xff800000
	v_mov_b32_e32 v100, 0xff800000
	s_and_saveexec_b64 vcc, s[96:97]
	s_cbranch_execz .LBB0_296
	ds_read_b128 v[100:103], v138 offset:11520
	ds_read_b128 v[104:107], v138 offset:11584
	v_max_f32_e32 v94, v109, v109
	v_max_f32_e32 v108, v108, v108
	v_max_f32_e32 v3, v3, v3
	s_waitcnt lgkmcnt(1)
	v_mfma_f32_16x16x32_bf16 v[100:103], v[40:43], v[100:103], 0
	v_max_f32_e32 v0, v0, v0
	s_waitcnt lgkmcnt(0)
	v_mfma_f32_16x16x32_bf16 v[100:103], v[36:39], v[104:107], v[100:103]
	s_nop 7
	v_mul_f32_e32 v86, 0x3e000000, v100
	v_cndmask_b32_e64 v86, v86, v168, s[24:25]
	v_mul_f32_e32 v99, 0x3e000000, v101
	v_mul_f32_e32 v100, 0x3e000000, v102
	v_max_f32_e32 v109, v94, v86
	v_mul_f32_e32 v94, 0x3e000000, v103
	v_cndmask_b32_e64 v101, v99, v168, s[26:27]
	v_cndmask_b32_e64 v99, v100, v168, s[28:29]
	v_cndmask_b32_e64 v100, v94, v168, s[30:31]
	v_max_f32_e32 v108, v108, v101
	v_max_f32_e32 v3, v3, v99
	v_max_f32_e32 v0, v0, v100
.LBB0_296:
	s_or_b64 exec, exec, vcc
	v_mov_b32_e32 v94, 0xff800000
	v_mov_b32_e32 v106, 0xff800000
	v_mov_b32_e32 v105, 0xff800000
	v_mov_b32_e32 v103, 0xff800000
	v_mov_b32_e32 v104, 0xff800000
	s_and_saveexec_b64 vcc, s[12:13]
	s_cbranch_execz .LBB0_298
	ds_read_b128 v[102:105], v138 offset:13824
	ds_read_b128 v[110:113], v138 offset:13888
	v_max_f32_e32 v109, v109, v109
	v_max_f32_e32 v108, v108, v108
	v_max_f32_e32 v3, v3, v3
	s_waitcnt lgkmcnt(1)
	v_mfma_f32_16x16x32_bf16 v[102:105], v[40:43], v[102:105], 0
	v_max_f32_e32 v0, v0, v0
	s_waitcnt lgkmcnt(0)
	v_mfma_f32_16x16x32_bf16 v[104:107], v[36:39], v[110:113], v[102:105]
	s_nop 7
	v_mul_f32_e32 v102, 0x3e000000, v104
	v_mul_f32_e32 v103, 0x3e000000, v105
	v_mul_f32_e32 v104, 0x3e000000, v106
	v_cndmask_b32_e64 v106, v102, v168, s[54:55]
	v_mul_f32_e32 v102, 0x3e000000, v107
	v_cndmask_b32_e64 v105, v103, v168, s[58:59]
	v_cndmask_b32_e64 v103, v104, v168, s[60:61]
	v_cndmask_b32_e64 v104, v102, v168, s[62:63]
	v_max_f32_e32 v109, v109, v106
	v_max_f32_e32 v108, v108, v105
	v_max_f32_e32 v3, v3, v103
	v_max_f32_e32 v0, v0, v104
.LBB0_298:
	s_or_b64 exec, exec, vcc
	v_mov_b32_e32 v113, 0xff800000
	v_mov_b32_e32 v107, 0xff800000
	v_mov_b32_e32 v112, 0xff800000
	s_and_saveexec_b64 vcc, s[22:23]
	s_cbranch_execz .LBB0_300
	ds_read_b128 v[110:113], v138 offset:16128
	ds_read_b128 v[114:117], v138 offset:16192
	v_max_f32_e32 v102, v109, v109
	v_max_f32_e32 v118, v108, v108
	v_max_f32_e32 v3, v3, v3
	s_waitcnt lgkmcnt(1)
	v_mfma_f32_16x16x32_bf16 v[110:113], v[40:43], v[110:113], 0
	v_max_f32_e32 v0, v0, v0
	s_waitcnt lgkmcnt(0)
	v_mfma_f32_16x16x32_bf16 v[108:111], v[36:39], v[114:117], v[110:113]
	s_nop 7
	v_mul_f32_e32 v94, 0x3e000000, v108
	v_cndmask_b32_e64 v94, v94, v168, s[68:69]
	v_mul_f32_e32 v107, 0x3e000000, v109
	v_mul_f32_e32 v108, 0x3e000000, v110
	v_max_f32_e32 v109, v102, v94
	v_mul_f32_e32 v102, 0x3e000000, v111
	v_cndmask_b32_e64 v113, v107, v168, s[70:71]
	v_cndmask_b32_e64 v107, v108, v168, s[72:73]
	v_cndmask_b32_e64 v112, v102, v168, s[74:75]
	v_max_f32_e32 v108, v118, v113
	v_max_f32_e32 v3, v3, v107
	v_max_f32_e32 v0, v0, v112
.LBB0_300:
	s_or_b64 exec, exec, vcc
	v_mov_b32_e32 v102, 0xff800000
	v_mov_b32_e32 v119, 0xff800000
	v_mov_b32_e32 v115, 0xff800000
	v_mov_b32_e32 v118, 0xff800000
	v_mov_b32_e32 v114, 0xff800000
	s_and_saveexec_b64 vcc, s[34:35]
	s_cbranch_execz .LBB0_302
	ds_read_b128 v[114:117], v138 offset:18432
	ds_read_b128 v[118:121], v138 offset:18496
	v_max_f32_e32 v122, v109, v109
	v_max_f32_e32 v123, v108, v108
	s_mov_b32 s88, 0x3e000000
	s_waitcnt lgkmcnt(1)
	v_mfma_f32_16x16x32_bf16 v[114:117], v[40:43], v[114:117], 0
	v_max_f32_e32 v3, v3, v3
	v_max_f32_e32 v0, v0, v0
	s_waitcnt lgkmcnt(0)
	v_mfma_f32_16x16x32_bf16 v[108:111], v[36:39], v[118:121], v[114:117]
	s_nop 7
	v_pk_mul_f32 v[108:109], v[108:109], s[88:89] op_sel_hi:[1,0]
	v_pk_mul_f32 v[110:111], v[110:111], s[88:89] op_sel_hi:[1,0]
	v_readlane_b32 s88, v237, 16
	v_readlane_b32 s89, v237, 17
	s_nop 1
	v_cndmask_b32_e64 v115, v109, v168, s[88:89]
	v_readlane_b32 s88, v237, 14
	v_readlane_b32 s89, v237, 15
	s_nop 1
	v_cndmask_b32_e64 v119, v108, v168, s[88:89]
	v_readlane_b32 s88, v237, 18
	v_readlane_b32 s89, v237, 19
	v_max_f32_e32 v109, v122, v119
	v_max_f32_e32 v108, v123, v115
	v_cndmask_b32_e64 v114, v111, v168, s[88:89]
	v_readlane_b32 s88, v237, 20
	v_readlane_b32 s89, v237, 21
	v_max_f32_e32 v0, v0, v114
	s_nop 0
	v_cndmask_b32_e64 v118, v110, v168, s[88:89]
	v_max_f32_e32 v3, v3, v118
; __device__ __forceinline__ void swa_phase(const bf16* QKV, bf16* MIX, const float* sinks, unsigned char* lds) {
;     ...
;             for (int kt = 0; kt < 16; ++kt) {
;                 if (kt >= wave && kt <= wave + 8) {
;                     acc[kt] = (f32x4){0.f, 0.f, 0.f, 0.f};
; #pragma unroll
;                     for (int ks = 0; ks < 2; ++ks) acc[kt] = __builtin_amdgcn_mfma_f32_16x16x32_bf16(qf[ks], *(const bf16x8*)(Ks + (16 * kt + r16) * 72 + 32 * ks + q4 * 8), acc[kt], 0, 0, 0);
; #pragma unroll
;                     for (int jj = 0; jj < 4; ++jj) { const int qi = 16 * wave + q4 * 4 + jj, kj = 16 * kt + r16, rel = qi + 128 - kj;
;                         const bool valid = (rel >= 0) && (rel < 128) && ((n > 0) || (kj >= 128));
;                         const float sv = valid ? acc[kt][jj] * 0.125f : -INFINITY; acc[kt][jj] = sv; mx[jj] = fmaxf(mx[jj], sv); }
;                 } else acc[kt] = (f32x4){-INFINITY, -INFINITY, -INFINITY, -INFINITY};
;             }
.LBB0_302:
	s_or_b64 exec, exec, vcc
	v_mov_b32_e32 v128, 0xff800000
	v_mov_b32_e32 v129, 0xff800000
	v_mov_b32_e32 v125, 0xff800000
	s_and_saveexec_b64 vcc, s[40:41]
	s_cbranch_execz .LBB0_304
	ds_read_b128 v[120:123], v138 offset:20736
	ds_read_b128 v[124:127], v138 offset:20800
	v_max_f32_e32 v116, v109, v109
	v_max_f32_e32 v117, v108, v108
	s_mov_b32 s88, 0x3e000000
	s_waitcnt lgkmcnt(1)
	v_mfma_f32_16x16x32_bf16 v[120:123], v[40:43], v[120:123], 0
	v_max_f32_e32 v3, v3, v3
	v_max_f32_e32 v0, v0, v0
	s_waitcnt lgkmcnt(0)
	v_mfma_f32_16x16x32_bf16 v[108:111], v[36:39], v[124:127], v[120:123]
	s_nop 7
	v_pk_mul_f32 v[108:109], v[108:109], s[88:89] op_sel_hi:[1,0]
	v_pk_mul_f32 v[110:111], v[110:111], s[88:89] op_sel_hi:[1,0]
	v_readlane_b32 s88, v237, 22
	v_readlane_b32 s89, v237, 23
	s_nop 1
	v_cndmask_b32_e64 v128, v109, v168, s[88:89]
	v_readlane_b32 s88, v237, 24
	v_readlane_b32 s89, v237, 25
	s_nop 1
	v_cndmask_b32_e64 v102, v108, v168, s[88:89]
	v_readlane_b32 s88, v237, 26
	v_readlane_b32 s89, v237, 27
	v_max_f32_e32 v109, v116, v102
	v_max_f32_e32 v108, v117, v128
	v_cndmask_b32_e64 v125, v111, v168, s[88:89]
	v_readlane_b32 s88, v237, 28
	v_readlane_b32 s89, v237, 29
	v_max_f32_e32 v0, v0, v125
	s_nop 0
	v_cndmask_b32_e64 v129, v110, v168, s[88:89]
	v_max_f32_e32 v3, v3, v129
.LBB0_304:
	s_or_b64 exec, exec, vcc
	v_mov_b32_e32 v124, 0xff800000
	v_mov_b32_e32 v148, 0xff800000
	v_mov_b32_e32 v145, 0xff800000
	v_mov_b32_e32 v147, 0xff800000
	v_mov_b32_e32 v144, 0xff800000
	s_and_saveexec_b64 vcc, s[52:53]
	s_cbranch_execz .LBB0_306
	ds_read_b128 v[120:123], v138 offset:23040
	ds_read_b128 v[130:133], v138 offset:23104
	v_max_f32_e32 v116, v109, v109
	v_max_f32_e32 v117, v108, v108
	s_mov_b32 s88, 0x3e000000
	s_waitcnt lgkmcnt(1)
	v_mfma_f32_16x16x32_bf16 v[120:123], v[40:43], v[120:123], 0
	v_max_f32_e32 v3, v3, v3
	v_max_f32_e32 v0, v0, v0
	s_waitcnt lgkmcnt(0)
	v_mfma_f32_16x16x32_bf16 v[108:111], v[36:39], v[130:133], v[120:123]
	s_nop 7
	v_pk_mul_f32 v[108:109], v[108:109], s[88:89] op_sel_hi:[1,0]
	v_pk_mul_f32 v[110:111], v[110:111], s[88:89] op_sel_hi:[1,0]
	v_readlane_b32 s88, v237, 30
	v_readlane_b32 s89, v237, 31
	s_nop 1
	v_cndmask_b32_e64 v145, v109, v168, s[88:89]
	v_readlane_b32 s88, v237, 32
	v_readlane_b32 s89, v237, 33
	s_nop 1
	v_cndmask_b32_e64 v148, v108, v168, s[88:89]
	v_readlane_b32 s88, v237, 34
	v_readlane_b32 s89, v237, 35
	v_max_f32_e32 v109, v116, v148
	v_max_f32_e32 v108, v117, v145
	v_cndmask_b32_e64 v144, v111, v168, s[88:89]
	v_readlane_b32 s88, v237, 36
	v_readlane_b32 s89, v237, 37
	v_max_f32_e32 v0, v0, v144
	s_nop 0
	v_cndmask_b32_e64 v147, v110, v168, s[88:89]
	v_max_f32_e32 v3, v3, v147
.LBB0_306:
	s_or_b64 exec, exec, vcc
	v_mov_b32_e32 v151, 0xff800000
	v_mov_b32_e32 v152, 0xff800000
	v_mov_b32_e32 v150, 0xff800000
	s_and_saveexec_b64 vcc, s[64:65]
	s_cbranch_execz .LBB0_308
	ds_read_b128 v[120:123], v138 offset:25344
	ds_read_b128 v[130:133], v138 offset:25408
	v_max_f32_e32 v116, v109, v109
	v_max_f32_e32 v117, v108, v108
	s_mov_b32 s88, 0x3e000000
	s_waitcnt lgkmcnt(1)
	v_mfma_f32_16x16x32_bf16 v[120:123], v[40:43], v[120:123], 0
	v_max_f32_e32 v3, v3, v3
	v_max_f32_e32 v0, v0, v0
	s_waitcnt lgkmcnt(0)
	v_mfma_f32_16x16x32_bf16 v[108:111], v[36:39], v[130:133], v[120:123]
	s_nop 7
	v_pk_mul_f32 v[108:109], v[108:109], s[88:89] op_sel_hi:[1,0]
	v_pk_mul_f32 v[110:111], v[110:111], s[88:89] op_sel_hi:[1,0]
	v_readlane_b32 s88, v237, 38
	v_readlane_b32 s89, v237, 39
	s_nop 1
	v_cndmask_b32_e64 v151, v109, v168, s[88:89]
	v_readlane_b32 s88, v237, 40
	v_readlane_b32 s89, v237, 41
	s_nop 1
	v_cndmask_b32_e64 v124, v108, v168, s[88:89]
	v_readlane_b32 s88, v237, 42
	v_readlane_b32 s89, v237, 43
	v_max_f32_e32 v109, v116, v124
	v_max_f32_e32 v108, v117, v151
	v_cndmask_b32_e64 v150, v111, v168, s[88:89]
	v_readlane_b32 s88, v237, 44
	v_readlane_b32 s89, v237, 45
	v_max_f32_e32 v0, v0, v150
	s_nop 0
	v_cndmask_b32_e64 v152, v110, v168, s[88:89]
	v_max_f32_e32 v3, v3, v152
; __device__ __forceinline__ void swa_phase(const bf16* QKV, bf16* MIX, const float* sinks, unsigned char* lds) {
;     ...
;             for (int kt = 0; kt < 16; ++kt) {
;                 if (kt >= wave && kt <= wave + 8) {
;                     acc[kt] = (f32x4){0.f, 0.f, 0.f, 0.f};
; #pragma unroll
;                     for (int ks = 0; ks < 2; ++ks) acc[kt] = __builtin_amdgcn_mfma_f32_16x16x32_bf16(qf[ks], *(const bf16x8*)(Ks + (16 * kt + r16) * 72 + 32 * ks + q4 * 8), acc[kt], 0, 0, 0);
; #pragma unroll
;                     for (int jj = 0; jj < 4; ++jj) { const int qi = 16 * wave + q4 * 4 + jj, kj = 16 * kt + r16, rel = qi + 128 - kj;
;                         const bool valid = (rel >= 0) && (rel < 128) && ((n > 0) || (kj >= 128));
;                         const float sv = valid ? acc[kt][jj] * 0.125f : -INFINITY; acc[kt][jj] = sv; mx[jj] = fmaxf(mx[jj], sv); }
;                 } else acc[kt] = (f32x4){-INFINITY, -INFINITY, -INFINITY, -INFINITY};
;             }
.LBB0_308:
	s_or_b64 exec, exec, vcc
	v_mov_b32_e32 v149, 0xff800000
	v_mov_b32_e32 v157, 0xff800000
	v_mov_b32_e32 v155, 0xff800000
	v_mov_b32_e32 v156, 0xff800000
	v_mov_b32_e32 v154, 0xff800000
	s_and_saveexec_b64 vcc, s[78:79]
	s_cbranch_execz .LBB0_310
	ds_read_b128 v[120:123], v138 offset:27648
	ds_read_b128 v[130:133], v138 offset:27712
	v_max_f32_e32 v116, v109, v109
	v_max_f32_e32 v117, v108, v108
	s_mov_b32 s88, 0x3e000000
	s_waitcnt lgkmcnt(1)
	v_mfma_f32_16x16x32_bf16 v[120:123], v[40:43], v[120:123], 0
	v_max_f32_e32 v3, v3, v3
	v_max_f32_e32 v0, v0, v0
	s_waitcnt lgkmcnt(0)
	v_mfma_f32_16x16x32_bf16 v[108:111], v[36:39], v[130:133], v[120:123]
	s_nop 7
	v_pk_mul_f32 v[108:109], v[108:109], s[88:89] op_sel_hi:[1,0]
	v_pk_mul_f32 v[110:111], v[110:111], s[88:89] op_sel_hi:[1,0]
	v_readlane_b32 s88, v237, 46
	v_readlane_b32 s89, v237, 47
	s_nop 1
	v_cndmask_b32_e64 v155, v109, v168, s[88:89]
	v_readlane_b32 s88, v237, 48
	v_readlane_b32 s89, v237, 49
	s_nop 1
	v_cndmask_b32_e64 v157, v108, v168, s[88:89]
	v_readlane_b32 s88, v237, 50
	v_readlane_b32 s89, v237, 51
	v_max_f32_e32 v109, v116, v157
	v_max_f32_e32 v108, v117, v155
	v_cndmask_b32_e64 v154, v111, v168, s[88:89]
	v_readlane_b32 s88, v237, 52
	v_readlane_b32 s89, v237, 53
	v_max_f32_e32 v0, v0, v154
	s_nop 0
	v_cndmask_b32_e64 v156, v110, v168, s[88:89]
	v_max_f32_e32 v3, v3, v156
.LBB0_310:
	s_or_b64 exec, exec, vcc
	v_mov_b32_e32 v159, 0xff800000
	v_mov_b32_e32 v160, 0xff800000
	v_mov_b32_e32 v158, 0xff800000
	s_and_saveexec_b64 vcc, s[90:91]
	s_cbranch_execz .LBB0_312
	ds_read_b128 v[120:123], v138 offset:29952
	ds_read_b128 v[130:133], v138 offset:30016
	v_max_f32_e32 v116, v109, v109
	v_max_f32_e32 v117, v108, v108
	s_mov_b32 s88, 0x3e000000
	s_waitcnt lgkmcnt(1)
	v_mfma_f32_16x16x32_bf16 v[120:123], v[40:43], v[120:123], 0
	v_max_f32_e32 v3, v3, v3
	v_max_f32_e32 v0, v0, v0
	s_waitcnt lgkmcnt(0)
	v_mfma_f32_16x16x32_bf16 v[108:111], v[36:39], v[130:133], v[120:123]
	s_nop 7
	v_pk_mul_f32 v[108:109], v[108:109], s[88:89] op_sel_hi:[1,0]
	v_pk_mul_f32 v[110:111], v[110:111], s[88:89] op_sel_hi:[1,0]
	v_readlane_b32 s88, v237, 54
	v_readlane_b32 s89, v237, 55
	s_nop 1
	v_cndmask_b32_e64 v159, v109, v168, s[88:89]
	v_readlane_b32 s88, v237, 56
	v_readlane_b32 s89, v237, 57
	s_nop 1
	v_cndmask_b32_e64 v149, v108, v168, s[88:89]
	v_readlane_b32 s88, v237, 58
	v_readlane_b32 s89, v237, 59
	v_max_f32_e32 v109, v116, v149
	v_max_f32_e32 v108, v117, v159
	v_cndmask_b32_e64 v158, v111, v168, s[88:89]
	v_readlane_b32 s88, v237, 60
	v_readlane_b32 s89, v237, 61
	v_max_f32_e32 v0, v0, v158
	s_nop 0
	v_cndmask_b32_e64 v160, v110, v168, s[88:89]
	v_max_f32_e32 v3, v3, v160
.LBB0_312:
	s_or_b64 exec, exec, vcc
	v_mov_b32_e32 v153, 0xff800000
	v_mov_b32_e32 v176, 0xff800000
	v_mov_b32_e32 v174, 0xff800000
	v_mov_b32_e32 v175, 0xff800000
	v_mov_b32_e32 v161, 0xff800000
	s_and_saveexec_b64 vcc, s[8:9]
	s_cbranch_execz .LBB0_314
	ds_read_b128 v[120:123], v138 offset:32256
	ds_read_b128 v[130:133], v138 offset:32320
	v_max_f32_e32 v116, v109, v109
	v_max_f32_e32 v117, v108, v108
	s_mov_b32 s88, 0x3e000000
	s_waitcnt lgkmcnt(1)
	v_mfma_f32_16x16x32_bf16 v[120:123], v[40:43], v[120:123], 0
	v_max_f32_e32 v3, v3, v3
	v_max_f32_e32 v0, v0, v0
	s_waitcnt lgkmcnt(0)
	v_mfma_f32_16x16x32_bf16 v[108:111], v[36:39], v[130:133], v[120:123]
	s_nop 7
	v_pk_mul_f32 v[108:109], v[108:109], s[88:89] op_sel_hi:[1,0]
	v_pk_mul_f32 v[110:111], v[110:111], s[88:89] op_sel_hi:[1,0]
	v_readlane_b32 s88, v237, 62
	v_readlane_b32 s89, v237, 63
	s_nop 1
	v_cndmask_b32_e64 v174, v109, v168, s[88:89]
	v_readlane_b32 s88, v236, 0
	v_readlane_b32 s89, v236, 1
	s_nop 1
	v_cndmask_b32_e64 v176, v108, v168, s[88:89]
	v_readlane_b32 s88, v236, 2
	v_readlane_b32 s89, v236, 3
	v_max_f32_e32 v109, v116, v176
	v_max_f32_e32 v108, v117, v174
	v_cndmask_b32_e64 v161, v111, v168, s[88:89]
	v_readlane_b32 s88, v236, 4
	v_readlane_b32 s89, v236, 5
	v_max_f32_e32 v0, v0, v161
	s_nop 0
	v_cndmask_b32_e64 v175, v110, v168, s[88:89]
	v_max_f32_e32 v3, v3, v175
.LBB0_314:
	s_or_b64 exec, exec, vcc
	v_mov_b32_e32 v177, 0xff800000
	v_mov_b32_e32 v179, 0xff800000
	v_mov_b32_e32 v178, 0xff800000
	s_and_saveexec_b64 vcc, s[20:21]
	s_cbranch_execz .LBB0_316
	ds_read_b128 v[120:123], v138 offset:34560
	s_mov_b32 s88, 0x3e000000
	v_readlane_b32 s92, v236, 6
	v_readlane_b32 s93, v236, 7
	v_max_f32_e32 v3, v3, v3
	s_waitcnt lgkmcnt(0)
	v_mfma_f32_16x16x32_bf16 v[40:43], v[40:43], v[120:123], 0
	ds_read_b128 v[120:123], v138 offset:34624
	v_max_f32_e32 v0, v0, v0
	s_waitcnt lgkmcnt(0)
	v_mfma_f32_16x16x32_bf16 v[36:39], v[36:39], v[120:123], v[40:43]
	s_nop 7
	v_pk_mul_f32 v[36:37], v[36:37], s[88:89] op_sel_hi:[1,0]
	s_nop 0
	v_cndmask_b32_e64 v177, v37, v168, s[92:93]
	v_readlane_b32 s92, v236, 8
	v_readlane_b32 s93, v236, 9
	s_nop 1
	v_cndmask_b32_e64 v153, v36, v168, s[92:93]
	v_max_f32_e32 v36, v109, v109
	v_max_f32_e32 v109, v36, v153
	v_max_f32_e32 v36, v108, v108
	v_max_f32_e32 v108, v36, v177
	v_pk_mul_f32 v[36:37], v[38:39], s[88:89] op_sel_hi:[1,0]
	v_readlane_b32 s88, v236, 10
	v_readlane_b32 s89, v236, 11
	s_nop 1
	v_cndmask_b32_e64 v178, v37, v168, s[88:89]
	v_readlane_b32 s88, v236, 12
	v_readlane_b32 s89, v236, 13
	v_max_f32_e32 v0, v0, v178
	s_nop 0
	v_cndmask_b32_e64 v179, v36, v168, s[88:89]
	v_max_f32_e32 v3, v3, v179

; __device__ __forceinline__ unsigned f2bf(float f) { return pk2(f, f) & 0xffffu; }
; __device__ __forceinline__ float red16(float v) { v += dpp_mov<0xB1>(v); v += dpp_mov<0x4E>(v); v += dpp_mov<0x141>(v); v += dpp_mov<0x140>(v); return v; }
; __device__ __forceinline__ void ret_out_phase(const bf16* Z, const bf16* SP, bf16* MIX, unsigned char* lds) {
;     ...
;             for (int ks = 0; ks < 2; ++ks) o2[dt] = __builtin_amdgcn_mfma_f32_16x16x32_bf16(qf[ks], tr_frag(Ss, 72, 32 * ks, 16 * dt, lane), o2[dt], 0, 0, 0); }
; #pragma unroll
;         for (int jj = 0; jj < 4; ++jj) { const int i = 16 * wave + q4 * 4 + jj; const float qd = __expf((float)(i + 1) * lg);
;             float v[4]; float s = 0.f;
; #pragma unroll
;             for (int dt = 0; dt < 4; ++dt) { v[dt] = o[dt][jj] + qd * o2[dt][jj]; s += v[dt]; }
;             const float mean = red16(s) * (1.f / 64.f); float q = 0.f;
; #pragma unroll
;             for (int dt = 0; dt < 4; ++dt) { v[dt] -= mean; q += v[dt] * v[dt]; }
;             const float rstd = rsqrtf(red16(q) * (1.f / 64.f) + 1e-6f);
; #pragma unroll
;             for (int dt = 0; dt < 4; ++dt) Ps[i * 136 + 16 * dt + r16] = (bf16)f2bf(v[dt] * rstd); }
.LBB0_587:
	s_or_b64 exec, exec, s[82:83]
	ds_read_b64_tr_b16 v[134:135], v132 offset:55392
	ds_read_b64_tr_b16 v[136:137], v132 offset:55968
	s_nop 3
	v_mov_b32_e32 v56, v50
	v_mov_b32_e32 v57, v42
	s_mov_b32 s82, 0x800000
	v_mov_b32_e32 v42, v51
	s_waitcnt lgkmcnt(0)
	v_mfma_f32_16x16x32_bf16 v[22:25], v[22:25], v[134:137], 0
	ds_read_b64_tr_b16 v[134:135], v132 offset:60000
	ds_read_b64_tr_b16 v[136:137], v132 offset:60576
	s_movk_i32 s89, 0x1e00
	s_lshl_b32 s16, s86, 1
	s_waitcnt lgkmcnt(0)
	v_mfma_f32_16x16x32_bf16 v[18:21], v[18:21], v[134:137], v[22:25]
	v_mov_b32_e32 v134, v26
	s_nop 1
	v_mul_f32_e32 v22, v89, v122
	v_mul_f32_e32 v22, 0x3fb8aa3b, v22
	v_exp_f32_e32 v22, v22
	s_nop 1
	v_mov_b32_e32 v24, v18
	v_mov_b32_e32 v25, v46
	v_mov_b32_e32 v135, v34
	v_pk_fma_f32 v[24:25], v[22:23], v[24:25], v[56:57] op_sel_hi:[0,1,1]
	v_mov_b32_e32 v56, v30
	v_mov_b32_e32 v57, v38
	v_pk_fma_f32 v[22:23], v[22:23], v[56:57], v[134:135] op_sel_hi:[0,1,1]
	v_add_f32_e32 v18, 0, v22
	v_add_f32_e32 v18, v18, v23
	v_add_f32_e32 v18, v18, v25
	v_add_f32_e32 v18, v18, v24
	v_mov_b32_e32 v46, v19
	v_mov_b32_e32 v38, v31
	v_add_f32_dpp v18, v18, v18 quad_perm:[1,0,3,2] row_mask:0xf bank_mask:0xf bound_ctrl:1
	v_mov_b32_e32 v34, v27
	v_lshl_add_u64 v[30:31], s[84:85], 0, v[84:85]
	v_add_f32_dpp v18, v18, v18 quad_perm:[2,3,0,1] row_mask:0xf bank_mask:0xf bound_ctrl:1
	s_nop 1
	v_add_f32_dpp v18, v18, v18 row_half_mirror row_mask:0xf bank_mask:0xf bound_ctrl:1
	s_nop 1
	v_add_f32_dpp v18, v18, v18 row_mirror row_mask:0xf bank_mask:0xf bound_ctrl:1
	v_mul_f32_e32 v18, 0x3c800000, v18
	v_pk_add_f32 v[22:23], v[22:23], v[18:19] op_sel_hi:[1,0] neg_lo:[0,1] neg_hi:[0,1]
	v_pk_add_f32 v[24:25], v[24:25], v[18:19] op_sel_hi:[1,0] neg_lo:[0,1] neg_hi:[0,1]
	v_pk_mul_f32 v[56:57], v[22:23], v[22:23]
	v_pk_mul_f32 v[134:135], v[24:25], v[24:25]
	v_add_f32_e32 v18, v56, v57
	v_add_f32_e32 v18, v135, v18
	v_add_f32_e32 v18, v134, v18
	s_nop 1
	v_add_f32_dpp v18, v18, v18 quad_perm:[1,0,3,2] row_mask:0xf bank_mask:0xf bound_ctrl:1
	s_nop 1
	v_add_f32_dpp v18, v18, v18 quad_perm:[2,3,0,1] row_mask:0xf bank_mask:0xf bound_ctrl:1
	s_nop 1
	v_add_f32_dpp v18, v18, v18 row_half_mirror row_mask:0xf bank_mask:0xf bound_ctrl:1
	s_nop 1
	v_add_f32_dpp v18, v18, v18 row_mirror row_mask:0xf bank_mask:0xf bound_ctrl:1
	v_fmamk_f32 v18, v18, 0x3c800000, v164
	v_cmp_gt_f32_e32 vcc, s82, v18
	v_mul_f32_e32 v26, 0x4b800000, v18
	s_nop 0
	v_cndmask_b32_e32 v18, v18, v26, vcc
	v_rsq_f32_e32 v18, v18
	s_nop 0
	v_mul_f32_e32 v26, 0x45800000, v18
	v_cndmask_b32_e32 v18, v18, v26, vcc
	v_mul_f32_e32 v22, v22, v18
	v_cvt_pk_bf16_f32 v22, v22, v22
	ds_write_b16 v54, v22 offset:64512
	v_mul_f32_e32 v22, v23, v18
	v_cvt_pk_bf16_f32 v22, v22, v22
	ds_write_b16 v54, v22 offset:64544
	v_mul_f32_e32 v22, v25, v18
	v_mul_f32_e32 v18, v24, v18
	v_cvt_pk_bf16_f32 v18, v18, v18
	ds_write_b16 v54, v18 offset:64608
	v_mul_f32_e32 v18, v89, v123
	v_mul_f32_e32 v18, 0x3fb8aa3b, v18
	v_exp_f32_e32 v18, v18
	v_cvt_pk_bf16_f32 v22, v22, v22
	ds_write_b16 v54, v22 offset:64576
	v_pk_fma_f32 v[22:23], v[18:19], v[46:47], v[42:43] op_sel_hi:[0,1,1]
	v_pk_fma_f32 v[18:19], v[18:19], v[38:39], v[34:35] op_sel_hi:[0,1,1]
	v_add_f32_e32 v24, 0, v18
	v_add_f32_e32 v24, v24, v19
	v_add_f32_e32 v24, v24, v23
	v_add_f32_e32 v24, v24, v22
	s_nop 1
	v_add_f32_dpp v24, v24, v24 quad_perm:[1,0,3,2] row_mask:0xf bank_mask:0xf bound_ctrl:1
	s_nop 1
	v_add_f32_dpp v24, v24, v24 quad_perm:[2,3,0,1] row_mask:0xf bank_mask:0xf bound_ctrl:1
	s_nop 1
	v_add_f32_dpp v24, v24, v24 row_half_mirror row_mask:0xf bank_mask:0xf bound_ctrl:1
	s_nop 1
	v_add_f32_dpp v24, v24, v24 row_mirror row_mask:0xf bank_mask:0xf bound_ctrl:1
	v_mul_f32_e32 v24, 0x3c800000, v24
	v_pk_add_f32 v[18:19], v[18:19], v[24:25] op_sel_hi:[1,0] neg_lo:[0,1] neg_hi:[0,1]
	v_pk_add_f32 v[22:23], v[22:23], v[24:25] op_sel_hi:[1,0] neg_lo:[0,1] neg_hi:[0,1]
	v_pk_mul_f32 v[26:27], v[18:19], v[18:19]
	v_pk_mul_f32 v[24:25], v[22:23], v[22:23]
	v_add_f32_e32 v26, v26, v27
	v_add_f32_e32 v25, v25, v26
	v_add_f32_e32 v24, v24, v25
	v_mov_b32_e32 v26, v28
	v_mov_b32_e32 v27, v36
	v_add_f32_dpp v24, v24, v24 quad_perm:[1,0,3,2] row_mask:0xf bank_mask:0xf bound_ctrl:1
	v_mov_b32_e32 v36, v29
	v_mov_b64_e32 v[28:29], s[94:95]
	v_add_f32_dpp v24, v24, v24 quad_perm:[2,3,0,1] row_mask:0xf bank_mask:0xf bound_ctrl:1
	s_nop 1
	v_add_f32_dpp v24, v24, v24 row_half_mirror row_mask:0xf bank_mask:0xf bound_ctrl:1
	s_nop 1
	v_add_f32_dpp v24, v24, v24 row_mirror row_mask:0xf bank_mask:0xf bound_ctrl:1
	v_fmamk_f32 v24, v24, 0x3c800000, v164
	v_cmp_gt_f32_e32 vcc, s82, v24
	v_mul_f32_e32 v25, 0x4b800000, v24
	s_nop 0
	v_cndmask_b32_e32 v24, v24, v25, vcc
	v_rsq_f32_e32 v24, v24
	s_nop 0
	v_mul_f32_e32 v25, 0x45800000, v24
	v_cndmask_b32_e32 v24, v24, v25, vcc
	v_mul_f32_e32 v18, v18, v24
	v_cvt_pk_bf16_f32 v18, v18, v18
	ds_write_b16 v54, v18 offset:64784
	v_mul_f32_e32 v18, v19, v24
	v_cvt_pk_bf16_f32 v18, v18, v18
	ds_write_b16 v54, v18 offset:64816
	v_mul_f32_e32 v18, v23, v24
	v_cvt_pk_bf16_f32 v18, v18, v18
	ds_write_b16 v54, v18 offset:64848
	v_mul_f32_e32 v18, v22, v24
	v_cvt_pk_bf16_f32 v18, v18, v18
	ds_write_b16 v54, v18 offset:64880
	v_mul_f32_e32 v18, v89, v124
	v_mul_f32_e32 v18, 0x3fb8aa3b, v18
	v_exp_f32_e32 v18, v18
	v_mov_b32_e32 v22, v20
	v_mov_b32_e32 v23, v48
	v_mov_b32_e32 v24, v52
	v_mov_b32_e32 v25, v44
	v_pk_fma_f32 v[22:23], v[18:19], v[22:23], v[24:25] op_sel_hi:[0,1,1]
	v_mov_b32_e32 v24, v32
	v_mov_b32_e32 v25, v40
	v_pk_fma_f32 v[18:19], v[18:19], v[24:25], v[26:27] op_sel_hi:[0,1,1]
	v_add_f32_e32 v20, 0, v18
	v_add_f32_e32 v20, v20, v19
; __device__ __forceinline__ unsigned pk2(float lo, float hi) { unsigned r; asm("v_cvt_pk_bf16_f32 %0, %1, %2" : "=v"(r) : "v"(lo), "v"(hi)); return r; }
; __device__ __forceinline__ unsigned f2bf(float f) { return pk2(f, f) & 0xffffu; }
; __device__ __forceinline__ float sigmoidf_(float x) { return __builtin_amdgcn_rcpf(1.f + __builtin_amdgcn_exp2f(x * -1.4426950408889634f)); }
; __device__ __forceinline__ float red16(float v) { v += dpp_mov<0xB1>(v); v += dpp_mov<0x4E>(v); v += dpp_mov<0x141>(v); v += dpp_mov<0x140>(v); return v; }
; __device__ __forceinline__ void ret_out_phase(const bf16* Z, const bf16* SP, bf16* MIX, unsigned char* lds) {
;     ...
;         for (int jj = 0; jj < 4; ++jj) { const int i = 16 * wave + q4 * 4 + jj; const float qd = __expf((float)(i + 1) * lg);
;             float v[4]; float s = 0.f;
; #pragma unroll
;             for (int dt = 0; dt < 4; ++dt) { v[dt] = o[dt][jj] + qd * o2[dt][jj]; s += v[dt]; }
;             const float mean = red16(s) * (1.f / 64.f); float q = 0.f;
; #pragma unroll
;             for (int dt = 0; dt < 4; ++dt) { v[dt] -= mean; q += v[dt] * v[dt]; }
;             const float rstd = rsqrtf(red16(q) * (1.f / 64.f) + 1e-6f);
; #pragma unroll
;             for (int dt = 0; dt < 4; ++dt) Ps[i * 136 + 16 * dt + r16] = (bf16)f2bf(v[dt] * rstd); }
; #pragma unroll
;         for (int t2 = 0; t2 < 2; ++t2) { const int cidx = lane + 64 * t2, i = 16 * wave + (cidx >> 3), c8 = (cidx & 7) * 8;
;             const u32x4 ov = *(const u32x4*)(Ps + i * 136 + c8), gv = *(const u32x4*)(Z + (rowbase + i) * EVEN_IN + 1536 + h * 64 + c8); u32x4 w;
; #pragma unroll
;             for (int x = 0; x < 4; ++x) { const float g0 = __uint_as_float(gv[x] << 16), g1 = __uint_as_float(gv[x] & 0xffff0000u);
;                 w[x] = pk2(__uint_as_float(ov[x] << 16) * g0 * sigmoidf_(g0), __uint_as_float(ov[x] & 0xffff0000u) * g1 * sigmoidf_(g1)); }
;             *(u32x4*)(MIX + (rowbase + i) * DM + h * 64 + c8) = w; }
	v_add_f32_e32 v20, v20, v23
	v_add_f32_e32 v20, v20, v22
	v_mov_b32_e32 v48, v21
	v_mov_b32_e32 v44, v53
	v_add_f32_dpp v20, v20, v20 quad_perm:[1,0,3,2] row_mask:0xf bank_mask:0xf bound_ctrl:1
	v_mov_b32_e32 v40, v33
	s_nop 0
	v_add_f32_dpp v20, v20, v20 quad_perm:[2,3,0,1] row_mask:0xf bank_mask:0xf bound_ctrl:1
	s_nop 1
	v_add_f32_dpp v20, v20, v20 row_half_mirror row_mask:0xf bank_mask:0xf bound_ctrl:1
	s_nop 1
	v_add_f32_dpp v20, v20, v20 row_mirror row_mask:0xf bank_mask:0xf bound_ctrl:1
	v_mul_f32_e32 v20, 0x3c800000, v20
	v_pk_add_f32 v[18:19], v[18:19], v[20:21] op_sel_hi:[1,0] neg_lo:[0,1] neg_hi:[0,1]
	v_pk_add_f32 v[22:23], v[22:23], v[20:21] op_sel_hi:[1,0] neg_lo:[0,1] neg_hi:[0,1]
	v_pk_mul_f32 v[24:25], v[18:19], v[18:19]
	v_pk_mul_f32 v[26:27], v[22:23], v[22:23]
	v_add_f32_e32 v20, v24, v25
	v_add_f32_e32 v20, v27, v20
	v_add_f32_e32 v20, v26, v20
	v_lshl_add_u64 v[26:27], v[76:77], 0, s[16:17]
	s_nop 0
	v_add_f32_dpp v20, v20, v20 quad_perm:[1,0,3,2] row_mask:0xf bank_mask:0xf bound_ctrl:1
	s_nop 1
	v_add_f32_dpp v20, v20, v20 quad_perm:[2,3,0,1] row_mask:0xf bank_mask:0xf bound_ctrl:1
	s_nop 1
	v_add_f32_dpp v20, v20, v20 row_half_mirror row_mask:0xf bank_mask:0xf bound_ctrl:1
	s_nop 1
	v_add_f32_dpp v20, v20, v20 row_mirror row_mask:0xf bank_mask:0xf bound_ctrl:1
	v_fmamk_f32 v20, v20, 0x3c800000, v164
	v_cmp_gt_f32_e32 vcc, s82, v20
	v_mul_f32_e32 v24, 0x4b800000, v20
	s_nop 0
	v_cndmask_b32_e32 v20, v20, v24, vcc
	v_rsq_f32_e32 v20, v20
	s_nop 0
	v_mul_f32_e32 v24, 0x45800000, v20
	v_cndmask_b32_e32 v20, v20, v24, vcc
	v_mul_f32_e32 v18, v18, v20
	v_cvt_pk_bf16_f32 v18, v18, v18
	ds_write_b16 v54, v18 offset:65056
	v_mul_f32_e32 v18, v19, v20
	v_cvt_pk_bf16_f32 v18, v18, v18
	ds_write_b16 v54, v18 offset:65088
	v_mul_f32_e32 v18, v23, v20
	v_cvt_pk_bf16_f32 v18, v18, v18
	ds_write_b16 v54, v18 offset:65120
	v_mul_f32_e32 v18, v22, v20
	v_cvt_pk_bf16_f32 v18, v18, v18
	ds_write_b16 v54, v18 offset:65152
	v_mul_f32_e32 v18, v89, v125
	v_mul_f32_e32 v18, 0x3fb8aa3b, v18
	v_exp_f32_e32 v18, v18
	v_mov_b32_e32 v89, v1
	v_pk_fma_f32 v[20:21], v[18:19], v[48:49], v[44:45] op_sel_hi:[0,1,1]
	v_pk_fma_f32 v[18:19], v[18:19], v[40:41], v[36:37] op_sel_hi:[0,1,1]
	v_add_f32_e32 v22, 0, v18
	v_add_f32_e32 v22, v22, v19
	v_add_f32_e32 v22, v22, v21
	v_add_f32_e32 v22, v22, v20
	s_nop 1
	v_add_f32_dpp v22, v22, v22 quad_perm:[1,0,3,2] row_mask:0xf bank_mask:0xf bound_ctrl:1
	s_nop 1
	v_add_f32_dpp v22, v22, v22 quad_perm:[2,3,0,1] row_mask:0xf bank_mask:0xf bound_ctrl:1
	s_nop 1
	v_add_f32_dpp v22, v22, v22 row_half_mirror row_mask:0xf bank_mask:0xf bound_ctrl:1
	s_nop 1
	v_add_f32_dpp v22, v22, v22 row_mirror row_mask:0xf bank_mask:0xf bound_ctrl:1
	v_mul_f32_e32 v22, 0x3c800000, v22
	v_pk_add_f32 v[18:19], v[18:19], v[22:23] op_sel_hi:[1,0] neg_lo:[0,1] neg_hi:[0,1]
	v_pk_add_f32 v[20:21], v[20:21], v[22:23] op_sel_hi:[1,0] neg_lo:[0,1] neg_hi:[0,1]
	v_pk_mul_f32 v[24:25], v[18:19], v[18:19]
	v_pk_mul_f32 v[22:23], v[20:21], v[20:21]
	v_add_f32_e32 v24, v24, v25
	v_add_f32_e32 v23, v23, v24
	v_add_f32_e32 v22, v22, v23
	s_nop 1
	v_add_f32_dpp v22, v22, v22 quad_perm:[1,0,3,2] row_mask:0xf bank_mask:0xf bound_ctrl:1
	s_nop 1
	v_add_f32_dpp v22, v22, v22 quad_perm:[2,3,0,1] row_mask:0xf bank_mask:0xf bound_ctrl:1
	s_nop 1
	v_add_f32_dpp v22, v22, v22 row_half_mirror row_mask:0xf bank_mask:0xf bound_ctrl:1
	s_nop 1
	v_add_f32_dpp v22, v22, v22 row_mirror row_mask:0xf bank_mask:0xf bound_ctrl:1
	v_fmamk_f32 v22, v22, 0x3c800000, v164
	v_cmp_gt_f32_e32 vcc, s82, v22
	v_mul_f32_e32 v23, 0x4b800000, v22
	s_nop 0
	v_cndmask_b32_e32 v22, v22, v23, vcc
	v_rsq_f32_e32 v22, v22
	s_nop 0
	v_mul_f32_e32 v23, 0x45800000, v22
	v_cndmask_b32_e32 v22, v22, v23, vcc
	v_mul_f32_e32 v18, v18, v22
	v_cvt_pk_bf16_f32 v18, v18, v18
	ds_write_b16 v54, v18 offset:65328
	v_mul_f32_e32 v18, v19, v22
	v_cvt_pk_bf16_f32 v18, v18, v18
	ds_write_b16 v54, v18 offset:65360
	v_mul_f32_e32 v18, v21, v22
	v_cvt_pk_bf16_f32 v18, v18, v18
	ds_write_b16 v54, v18 offset:65392
	v_mul_f32_e32 v18, v20, v22
	v_mad_u64_u32 v[22:23], s[82:83], v30, s89, v[28:29]
	v_mov_b32_e32 v24, v23
	v_mad_u64_u32 v[24:25], s[82:83], v31, s89, v[24:25]
	v_mov_b32_e32 v23, v24
	v_lshl_add_u64 v[22:23], v[22:23], 0, s[16:17]
	v_lshl_add_u64 v[22:23], v[22:23], 0, v[88:89]
	global_load_dwordx4 v[22:25], v[22:23], off offset:3072
	v_lshl_add_u64 v[178:179], s[84:85], 0, v[86:87]
	v_mad_u64_u32 v[180:181], s[82:83], v178, s89, v[28:29]
	v_mov_b32_e32 v182, v181
	v_mad_u64_u32 v[182:183], s[82:83], v179, s89, v[182:183]
	v_mov_b32_e32 v181, v182
	v_lshl_add_u64 v[180:181], v[180:181], 0, s[16:17]
	v_lshl_add_u64 v[180:181], v[180:181], 0, v[88:89]
	global_load_dwordx4 v[174:177], v[180:181], off offset:3072
	v_cvt_pk_bf16_f32 v18, v18, v18
	ds_write_b16 v54, v18 offset:65424
	v_add_u32_e32 v18, v68, v126
	ds_read_b128 v[18:21], v18 offset:64512
	s_andn2_b64 vcc, exec, s[90:91]
	s_waitcnt lgkmcnt(0)
	v_lshlrev_b32_e32 v33, 16, v18
	v_and_b32_e32 v18, 0xffff0000, v18
	s_waitcnt vmcnt(1)
; __device__ __forceinline__ unsigned pk2(float lo, float hi) { unsigned r; asm("v_cvt_pk_bf16_f32 %0, %1, %2" : "=v"(r) : "v"(lo), "v"(hi)); return r; }
; __device__ __forceinline__ float sigmoidf_(float x) { return __builtin_amdgcn_rcpf(1.f + __builtin_amdgcn_exp2f(x * -1.4426950408889634f)); }
; __device__ __forceinline__ void ret_out_phase(const bf16* Z, const bf16* SP, bf16* MIX, unsigned char* lds) {
;     ...
;         for (int t2 = 0; t2 < 2; ++t2) { const int cidx = lane + 64 * t2, i = 16 * wave + (cidx >> 3), c8 = (cidx & 7) * 8;
;             const u32x4 ov = *(const u32x4*)(Ps + i * 136 + c8), gv = *(const u32x4*)(Z + (rowbase + i) * EVEN_IN + 1536 + h * 64 + c8); u32x4 w;
; #pragma unroll
;             for (int x = 0; x < 4; ++x) { const float g0 = __uint_as_float(gv[x] << 16), g1 = __uint_as_float(gv[x] & 0xffff0000u);
;                 w[x] = pk2(__uint_as_float(ov[x] << 16) * g0 * sigmoidf_(g0), __uint_as_float(ov[x] & 0xffff0000u) * g1 * sigmoidf_(g1)); }
;             *(u32x4*)(MIX + (rowbase + i) * DM + h * 64 + c8) = w; }
	v_lshlrev_b32_e32 v32, 16, v22
	v_and_b32_e32 v22, 0xffff0000, v22
	v_mul_f32_e32 v33, v32, v33
	v_mul_f32_e32 v32, 0xbfb8aa3b, v32
	v_mul_f32_e32 v18, v22, v18
	v_mul_f32_e32 v22, 0xbfb8aa3b, v22
	v_exp_f32_e32 v32, v32
	v_exp_f32_e32 v22, v22
	v_add_f32_e32 v32, 1.0, v32
	v_add_f32_e32 v22, 1.0, v22
	v_rcp_f32_e32 v32, v32
	v_rcp_f32_e32 v22, v22
	v_mul_f32_e32 v32, v33, v32
	v_mul_f32_e32 v18, v18, v22
	v_cvt_pk_bf16_f32 v18, v32, v18
	v_lshlrev_b32_e32 v22, 16, v23
	v_lshlrev_b32_e32 v32, 16, v19
	v_and_b32_e32 v23, 0xffff0000, v23
	v_and_b32_e32 v19, 0xffff0000, v19
	v_mul_f32_e32 v32, v22, v32
	v_mul_f32_e32 v22, 0xbfb8aa3b, v22
	v_mul_f32_e32 v19, v23, v19
	v_mul_f32_e32 v23, 0xbfb8aa3b, v23
	v_exp_f32_e32 v22, v22
	v_exp_f32_e32 v23, v23
	v_add_f32_e32 v22, 1.0, v22
	v_add_f32_e32 v23, 1.0, v23
	v_rcp_f32_e32 v22, v22
	v_rcp_f32_e32 v23, v23
	v_mul_f32_e32 v22, v32, v22
	v_mul_f32_e32 v19, v19, v23
	v_cvt_pk_bf16_f32 v19, v22, v19
	v_lshlrev_b32_e32 v22, 16, v24
	v_lshlrev_b32_e32 v23, 16, v20
	v_mul_f32_e32 v23, v22, v23
	v_mul_f32_e32 v22, 0xbfb8aa3b, v22
	v_exp_f32_e32 v22, v22
	v_and_b32_e32 v20, 0xffff0000, v20
	v_add_f32_e32 v22, 1.0, v22
	v_rcp_f32_e32 v22, v22
	s_nop 0
	v_mul_f32_e32 v22, v23, v22
	v_and_b32_e32 v23, 0xffff0000, v24
	v_mul_f32_e32 v20, v23, v20
	v_mul_f32_e32 v23, 0xbfb8aa3b, v23
	v_exp_f32_e32 v23, v23
	s_nop 0
	v_add_f32_e32 v23, 1.0, v23
	v_rcp_f32_e32 v23, v23
	s_nop 0
	v_mul_f32_e32 v20, v20, v23
	v_cvt_pk_bf16_f32 v20, v22, v20
	v_lshlrev_b32_e32 v22, 16, v25
	v_lshlrev_b32_e32 v23, 16, v21
	v_mul_f32_e32 v23, v22, v23
	v_mul_f32_e32 v22, 0xbfb8aa3b, v22
	v_exp_f32_e32 v22, v22
	v_and_b32_e32 v21, 0xffff0000, v21
	v_add_f32_e32 v22, 1.0, v22
	v_rcp_f32_e32 v22, v22
	s_nop 0
	v_mul_f32_e32 v22, v23, v22
	v_and_b32_e32 v23, 0xffff0000, v25
	v_mul_f32_e32 v21, v23, v21
	v_mul_f32_e32 v23, 0xbfb8aa3b, v23
	v_exp_f32_e32 v23, v23
	s_nop 0
	v_add_f32_e32 v23, 1.0, v23
	v_rcp_f32_e32 v23, v23
	s_nop 0
	v_mul_f32_e32 v21, v21, v23
	v_cvt_pk_bf16_f32 v21, v22, v21
	v_lshlrev_b64 v[22:23], 11, v[30:31]
	v_lshl_add_u64 v[22:23], v[26:27], 0, v[22:23]
	global_store_dwordx4 v[22:23], v[18:21], off
	ds_read_b128 v[20:23], v130 offset:64512
	s_nop 0
	v_lshl_add_u64 v[18:19], s[84:85], 0, v[86:87]
	v_mad_u64_u32 v[24:25], s[82:83], v18, s89, v[28:29]
	v_mov_b32_e32 v28, v25
	v_mad_u64_u32 v[28:29], s[82:83], v19, s89, v[28:29]
	v_mov_b32_e32 v25, v28
	v_lshl_add_u64 v[24:25], v[24:25], 0, s[16:17]
	v_lshl_add_u64 v[24:25], v[24:25], 0, v[88:89]
	s_waitcnt lgkmcnt(0)
	v_lshlrev_b32_e32 v25, 16, v20
	v_and_b32_e32 v20, 0xffff0000, v20
	v_lshlrev_b64 v[18:19], 11, v[18:19]
	v_readlane_b32 s82, v240, 40
	v_lshl_add_u64 v[18:19], v[26:27], 0, v[18:19]
	s_add_i32 s96, s96, s82
	s_waitcnt vmcnt(1)
	v_mov_b64_e32 v[28:29], v[174:175]
	v_mov_b64_e32 v[30:31], v[176:177]
	v_lshlrev_b32_e32 v24, 16, v28
	v_mul_f32_e32 v25, v24, v25
	v_mul_f32_e32 v24, 0xbfb8aa3b, v24
	v_exp_f32_e32 v24, v24
	s_nop 0
	v_add_f32_e32 v24, 1.0, v24
	v_rcp_f32_e32 v24, v24
	s_nop 0
	v_mul_f32_e32 v24, v25, v24
	v_and_b32_e32 v25, 0xffff0000, v28
	v_mul_f32_e32 v20, v25, v20
	v_mul_f32_e32 v25, 0xbfb8aa3b, v25
	v_exp_f32_e32 v25, v25
	s_nop 0
	v_add_f32_e32 v25, 1.0, v25
	v_rcp_f32_e32 v25, v25
	s_nop 0
	v_mul_f32_e32 v20, v20, v25
	v_cvt_pk_bf16_f32 v20, v24, v20
	v_lshlrev_b32_e32 v24, 16, v29
	v_lshlrev_b32_e32 v25, 16, v21
	v_mul_f32_e32 v25, v24, v25
	v_mul_f32_e32 v24, 0xbfb8aa3b, v24
	v_exp_f32_e32 v24, v24
	v_and_b32_e32 v21, 0xffff0000, v21
	v_add_f32_e32 v24, 1.0, v24
	v_rcp_f32_e32 v24, v24
	s_nop 0
	v_mul_f32_e32 v24, v25, v24
	v_and_b32_e32 v25, 0xffff0000, v29
	v_mul_f32_e32 v21, v25, v21
	v_mul_f32_e32 v25, 0xbfb8aa3b, v25
	v_exp_f32_e32 v25, v25
	s_nop 0
	v_add_f32_e32 v25, 1.0, v25
	v_rcp_f32_e32 v25, v25
	s_nop 0
	v_mul_f32_e32 v21, v21, v25
	v_cvt_pk_bf16_f32 v21, v24, v21
	v_lshlrev_b32_e32 v24, 16, v30
	v_lshlrev_b32_e32 v25, 16, v22
	v_mul_f32_e32 v25, v24, v25
	v_mul_f32_e32 v24, 0xbfb8aa3b, v24
	v_exp_f32_e32 v24, v24
	v_and_b32_e32 v22, 0xffff0000, v22
	v_add_f32_e32 v24, 1.0, v24
	v_rcp_f32_e32 v24, v24
	s_nop 0
	v_mul_f32_e32 v24, v25, v24
	v_and_b32_e32 v25, 0xffff0000, v30
	v_mul_f32_e32 v22, v25, v22
	v_mul_f32_e32 v25, 0xbfb8aa3b, v25
	v_exp_f32_e32 v25, v25
	s_nop 0
	v_add_f32_e32 v25, 1.0, v25
	v_rcp_f32_e32 v25, v25
	s_nop 0
	v_mul_f32_e32 v22, v22, v25
	v_cvt_pk_bf16_f32 v22, v24, v22
	v_lshlrev_b32_e32 v24, 16, v31
	v_lshlrev_b32_e32 v25, 16, v23
	v_mul_f32_e32 v25, v24, v25
	v_mul_f32_e32 v24, 0xbfb8aa3b, v24
	v_exp_f32_e32 v24, v24
	v_and_b32_e32 v23, 0xffff0000, v23
	v_add_f32_e32 v24, 1.0, v24
	v_rcp_f32_e32 v24, v24
	s_nop 0
	v_mul_f32_e32 v24, v25, v24
	v_and_b32_e32 v25, 0xffff0000, v31
	v_mul_f32_e32 v23, v25, v23
	v_mul_f32_e32 v25, 0xbfb8aa3b, v25
	v_exp_f32_e32 v25, v25
	s_nop 0
	v_add_f32_e32 v25, 1.0, v25
	v_rcp_f32_e32 v25, v25
	s_nop 0
	v_mul_f32_e32 v23, v23, v25
	v_cvt_pk_bf16_f32 v23, v24, v23
	global_store_dwordx4 v[18:19], v[20:23], off
	s_cbranch_vccz .LBB0_638

; __device__ __forceinline__ void rwkv_out_phase(const bf16* Z, const RwkvW w, const bf16* Wl, const float* Ub, const bf16* RHO, const bf16* Y0, const float* BON, bf16* MIX, unsigned char* lds) {
;     ...
;         f32x4 ya[4], ga[4];
; #pragma unroll
;         for (int dt = 0; dt < 4; ++dt) { ya[dt] = (f32x4){0.f, 0.f, 0.f, 0.f}; ga[dt] = (f32x4){0.f, 0.f, 0.f, 0.f};
; #pragma unroll
;             for (int k0 = 0; k0 < 64; k0 += 32) ya[dt] = mma16(Rs, 72, 16 * wave, Ss, 72, 16 * dt, k0, ya[dt], lane);
;             const bf16* wg = Wl + (size_t)(1024 + col0 + 16 * dt + r16) * 256 + 128 + q4 * 8;
; #pragma unroll
;             for (int ks = 0; ks < 4; ++ks) ga[dt] = __builtin_amdgcn_mfma_f32_16x16x32_bf16(*(const bf16x8*)(AG + (16 * wave + r16) * 136 + 32 * ks + q4 * 8), *(const bf16x8*)(wg + 32 * ks), ga[dt], 0, 0, 0); }
.LBB0_641:
	s_or_b64 exec, exec, s[18:19]
	s_waitcnt lgkmcnt(0)
	s_barrier
	ds_read_b128 v[30:33], v52
	ds_read_b128 v[2:5], v102 offset:18432
	v_or_b32_e32 v69, s37, v73
	s_waitcnt lgkmcnt(0)
	v_mfma_f32_16x16x32_bf16 v[6:9], v[30:33], v[2:5], 0
	ds_read_b128 v[2:5], v52 offset:64
	ds_read_b128 v[10:13], v102 offset:18496
	v_lshlrev_b32_e32 v0, 9, v69
	v_mov_b32_e32 v67, v1
	s_waitcnt lgkmcnt(0)
	v_mfma_f32_16x16x32_bf16 v[18:21], v[2:5], v[10:13], v[6:9]
	s_mov_b64 s[18:19], 0x80100
	s_nop 1
	v_lshl_add_u64 v[6:7], s[12:13], 0, v[0:1]
	v_lshl_add_u64 v[70:71], v[6:7], 0, v[66:67]
	s_mov_b64 s[20:21], 0x80000
	v_lshl_add_u64 v[156:157], v[70:71], 0, s[20:21]
	s_mov_b64 s[20:21], 0x2000
	global_load_dwordx4 v[174:177], v[156:157], off offset:256
	global_load_dwordx4 v[178:181], v[156:157], off offset:320
	global_load_dwordx4 v[182:185], v[156:157], off offset:384
	global_load_dwordx4 v[186:189], v[156:157], off offset:448
	v_lshl_add_u64 v[156:157], v[156:157], 0, s[20:21]
	global_load_dwordx4 v[190:193], v[156:157], off offset:256
	global_load_dwordx4 v[194:197], v[156:157], off offset:320
	global_load_dwordx4 v[198:201], v[156:157], off offset:384
	global_load_dwordx4 v[202:205], v[156:157], off offset:448
	v_lshl_add_u64 v[156:157], v[156:157], 0, s[20:21]
	global_load_dwordx4 v[206:209], v[156:157], off offset:256
	global_load_dwordx4 v[210:213], v[156:157], off offset:320
	global_load_dwordx4 v[214:217], v[156:157], off offset:384
	global_load_dwordx4 v[218:221], v[156:157], off offset:448
	v_lshl_add_u64 v[156:157], v[156:157], 0, s[20:21]
	global_load_dwordx4 v[222:225], v[156:157], off offset:256
	global_load_dwordx4 v[226:229], v[156:157], off offset:320
	global_load_dwordx4 v[230:233], v[156:157], off offset:384
	global_load_dwordx4 v[114:117], v[156:157], off offset:448
	v_lshl_add_u64 v[14:15], v[70:71], 0, s[18:19]
	s_mov_b32 s18, 0x80000
	v_add_co_u32_e32 v6, vcc, s18, v70
	s_nop 0
	v_addc_co_u32_e32 v7, vcc, 0, v71, vcc
	ds_read_b128 v[38:41], v53 offset:27648
	ds_read_b128 v[34:37], v53 offset:27712
	ds_read_b128 v[42:45], v53 offset:27776
	ds_read_b128 v[46:49], v53 offset:27840
	s_mov_b64 s[18:19], 0x82100
	v_lshl_add_u64 v[26:27], v[70:71], 0, s[18:19]
	s_mov_b32 s18, 0x82000
	s_mov_b32 s20, 0x800000
	s_movk_i32 s21, 0x1000
	s_mov_b32 s25, s61
	s_waitcnt lgkmcnt(3)
	s_waitcnt vmcnt(15)
	v_mfma_f32_16x16x32_bf16 v[6:9], v[38:41], v[174:177], 0
	s_waitcnt lgkmcnt(2)
	s_waitcnt vmcnt(14)
	v_mfma_f32_16x16x32_bf16 v[6:9], v[34:37], v[178:181], v[6:9]
	s_waitcnt lgkmcnt(1)
	s_waitcnt vmcnt(13)
	v_mfma_f32_16x16x32_bf16 v[6:9], v[42:45], v[182:185], v[6:9]
	ds_read_b128 v[14:17], v102 offset:20800
	s_waitcnt lgkmcnt(1)
	s_waitcnt vmcnt(12)
	v_mfma_f32_16x16x32_bf16 v[6:9], v[46:49], v[186:189], v[6:9]
	ds_read_b128 v[10:13], v102 offset:20736
	s_waitcnt lgkmcnt(0)
	v_mfma_f32_16x16x32_bf16 v[10:13], v[30:33], v[10:13], 0
	v_mfma_f32_16x16x32_bf16 v[22:25], v[2:5], v[14:17], v[10:13]
	s_nop 5
	v_add_co_u32_e32 v10, vcc, s18, v70
	s_mov_b64 s[18:19], 0x84100
	s_nop 0
	v_addc_co_u32_e32 v11, vcc, 0, v71, vcc
	v_lshl_add_u64 v[112:113], v[70:71], 0, s[18:19]
	s_mov_b32 s18, 0x84000
	s_waitcnt vmcnt(11)
	v_mfma_f32_16x16x32_bf16 v[10:13], v[38:41], v[190:193], 0
	s_waitcnt vmcnt(10)
	v_mfma_f32_16x16x32_bf16 v[10:13], v[34:37], v[194:197], v[10:13]
	s_waitcnt vmcnt(9)
	v_mfma_f32_16x16x32_bf16 v[10:13], v[42:45], v[198:201], v[10:13]
	ds_read_b128 v[26:29], v102 offset:23104
	s_waitcnt vmcnt(8)
	v_mfma_f32_16x16x32_bf16 v[10:13], v[46:49], v[202:205], v[10:13]
	ds_read_b128 v[14:17], v102 offset:23040
	s_waitcnt lgkmcnt(0)
	v_mfma_f32_16x16x32_bf16 v[14:17], v[30:33], v[14:17], 0
	v_mfma_f32_16x16x32_bf16 v[26:29], v[2:5], v[26:29], v[14:17]
	s_nop 6
	v_add_co_u32_e32 v14, vcc, s18, v70
	s_mov_b64 s[18:19], 0x86100
	s_nop 0
	v_addc_co_u32_e32 v15, vcc, 0, v71, vcc
	s_waitcnt vmcnt(7)
	v_mfma_f32_16x16x32_bf16 v[14:17], v[38:41], v[206:209], 0
	s_waitcnt vmcnt(6)
	v_mfma_f32_16x16x32_bf16 v[14:17], v[34:37], v[210:213], v[14:17]
	s_waitcnt vmcnt(5)
	v_mfma_f32_16x16x32_bf16 v[14:17], v[42:45], v[214:217], v[14:17]
	s_waitcnt vmcnt(4)
	v_mfma_f32_16x16x32_bf16 v[14:17], v[46:49], v[218:221], v[14:17]
	ds_read_b128 v[108:111], v102 offset:25344
	s_waitcnt lgkmcnt(0)
	v_mfma_f32_16x16x32_bf16 v[30:33], v[30:33], v[108:111], 0
	ds_read_b128 v[108:111], v102 offset:25408
	s_waitcnt lgkmcnt(0)
	v_mfma_f32_16x16x32_bf16 v[30:33], v[2:5], v[108:111], v[30:33]
	v_lshl_add_u64 v[108:109], v[70:71], 0, s[18:19]
	s_mov_b32 s18, 0x86000
	v_add_co_u32_e32 v2, vcc, s18, v70
	s_lshl_b32 s18, s38, 2
	s_nop 0
	v_addc_co_u32_e32 v3, vcc, 0, v71, vcc
	s_add_u32 s18, s35, s18
	s_addc_u32 s19, s36, 0
	s_lshl_b32 s60, s37, 1
	s_add_i32 s26, s26, s70
	s_cmpk_gt_i32 s26, 0x7ff
	s_waitcnt vmcnt(3)
	v_mfma_f32_16x16x32_bf16 v[2:5], v[38:41], v[222:225], 0
	s_waitcnt vmcnt(2)
	v_mfma_f32_16x16x32_bf16 v[2:5], v[34:37], v[226:229], v[2:5]
	v_mov_b32_e32 v38, v18
	v_mov_b32_e32 v39, v22
	s_waitcnt vmcnt(1)
	v_mfma_f32_16x16x32_bf16 v[2:5], v[42:45], v[230:233], v[2:5]
	s_waitcnt vmcnt(0)
; __device__ __forceinline__ float bf2f(bf16 v) { return __uint_as_float(((unsigned)v) << 16); }
; __device__ __forceinline__ unsigned f2bf(float f) { return pk2(f, f) & 0xffffu; }
; __device__ __forceinline__ float red16(float v) { v += dpp_mov<0xB1>(v); v += dpp_mov<0x4E>(v); v += dpp_mov<0x141>(v); v += dpp_mov<0x140>(v); return v; }
; __device__ __forceinline__ void rwkv_out_phase(const bf16* Z, const RwkvW w, const bf16* Wl, const float* Ub, const bf16* RHO, const bf16* Y0, const float* BON, bf16* MIX, unsigned char* lds) {
;     ...
;         for (int jj = 0; jj < 4; ++jj) { const int tl = 16 * wave + q4 * 4 + jj; const float bon = BON[(rowbase + tl) * 8 + h];
;             float y[4]; float sum = 0.f;
; #pragma unroll
;             for (int dt = 0; dt < 4; ++dt) { y[dt] = ya[dt][jj] + bf2f(Ys[tl * 72 + 16 * dt + r16]); sum += y[dt]; }
;             const float mean = red16(sum) * (1.f / 64.f); float qq = 0.f;
; #pragma unroll
;             for (int dt = 0; dt < 4; ++dt) { y[dt] -= mean; qq += y[dt] * y[dt]; }
;             const float rstd = rsqrtf(red16(qq) * (1.f / 64.f) + 64e-5f);
; #pragma unroll
;             for (int dt = 0; dt < 4; ++dt) { const int ch = 16 * dt + r16; const float vc = bf2f(Vs[(tl + 1) * 72 + ch]), vp = bf2f(Vs[tl * 72 + ch]);
;                 const float vs = vc + w.mu[1024 + col0 + ch] * (vp - vc);
;                 Ys[tl * 72 + ch] = (bf16)f2bf((y[dt] * rstd * w.ln_g[col0 + ch] + w.ln_b[col0 + ch] + bon * vs) * ga[dt][jj]); } }
	v_mfma_f32_16x16x32_bf16 v[2:5], v[46:49], v[114:117], v[2:5]
	v_lshl_add_u64 v[34:35], s[16:17], 0, v[54:55]
	v_lshlrev_b64 v[34:35], 5, v[34:35]
	v_lshl_add_u64 v[34:35], s[18:19], 0, v[34:35]
	global_load_dword v43, v[34:35], off
	v_add_lshl_u32 v118, s37, v73, 2
	v_mov_b32_e32 v119, 0
	global_load_dword v120, v118, s[8:9]
	global_load_dword v121, v118, s[10:11]
	global_load_dword v122, v118, s[8:9] offset:64
	global_load_dword v123, v118, s[10:11] offset:64
	global_load_dword v138, v118, s[8:9] offset:128
	global_load_dword v139, v118, s[10:11] offset:128
	global_load_dword v140, v118, s[8:9] offset:192
	global_load_dword v141, v118, s[10:11] offset:192
	v_lshl_add_u64 v[124:125], s[6:7], 0, v[118:119]
	v_add_co_u32_e32 v124, vcc, 0x1000, v124
	s_nop 1
	v_addc_co_u32_e32 v125, vcc, 0, v125, vcc
	global_load_dword v126, v[124:125], off
	global_load_dword v127, v[124:125], off offset:64
	global_load_dword v128, v[124:125], off offset:128
	global_load_dword v129, v[124:125], off offset:192
	v_lshl_add_u64 v[136:137], s[16:17], 0, v[58:59]
	v_lshlrev_b64 v[136:137], 5, v[136:137]
	v_lshl_add_u64 v[136:137], s[18:19], 0, v[136:137]
	global_load_dword v132, v[136:137], off
	v_lshl_add_u64 v[136:137], s[16:17], 0, v[60:61]
	v_lshlrev_b64 v[136:137], 5, v[136:137]
	v_lshl_add_u64 v[136:137], s[18:19], 0, v[136:137]
	global_load_dword v133, v[136:137], off
	v_lshl_add_u64 v[136:137], s[16:17], 0, v[62:63]
	v_lshlrev_b64 v[136:137], 5, v[136:137]
	v_lshl_add_u64 v[136:137], s[18:19], 0, v[136:137]
	global_load_dword v134, v[136:137], off
	ds_read_u16 v0, v103 offset:62560
	ds_read_u16 v34, v103 offset:62528
	v_mov_b32_e32 v37, v26
	v_mov_b32_e32 v36, v30
	s_waitcnt lgkmcnt(0)
	v_lshlrev_b32_e32 v35, 16, v34
	v_lshlrev_b32_e32 v34, 16, v0
	ds_read_u16 v0, v103 offset:62464
	ds_read_u16 v26, v103 offset:62496
	v_pk_add_f32 v[34:35], v[36:37], v[34:35]
	s_waitcnt lgkmcnt(1)
	v_lshlrev_b32_e32 v36, 16, v0
	s_waitcnt lgkmcnt(0)
	v_lshlrev_b32_e32 v37, 16, v26
	v_pk_add_f32 v[36:37], v[38:39], v[36:37]
	s_nop 0
	v_add_f32_e32 v0, 0, v36
	v_add_f32_e32 v0, v0, v37
	v_add_f32_e32 v0, v0, v35
	v_add_f32_e32 v0, v0, v34
	s_nop 1
	v_add_f32_dpp v0, v0, v0 quad_perm:[1,0,3,2] row_mask:0xf bank_mask:0xf bound_ctrl:1
	s_nop 1
	v_add_f32_dpp v0, v0, v0 quad_perm:[2,3,0,1] row_mask:0xf bank_mask:0xf bound_ctrl:1
	s_nop 1
	v_add_f32_dpp v0, v0, v0 row_half_mirror row_mask:0xf bank_mask:0xf bound_ctrl:1
	s_nop 1
	v_add_f32_dpp v0, v0, v0 row_mirror row_mask:0xf bank_mask:0xf bound_ctrl:1
	v_mul_f32_e32 v0, 0x3c800000, v0
	v_pk_add_f32 v[36:37], v[36:37], v[0:1] op_sel_hi:[1,0] neg_lo:[0,1] neg_hi:[0,1]
	v_pk_add_f32 v[34:35], v[34:35], v[0:1] op_sel_hi:[1,0] neg_lo:[0,1] neg_hi:[0,1]
	v_pk_mul_f32 v[38:39], v[36:37], v[36:37]
	v_pk_mul_f32 v[40:41], v[34:35], v[34:35]
	v_add_f32_e32 v0, v38, v39
	v_add_f32_e32 v0, v41, v0
	v_add_f32_e32 v0, v40, v0
	s_nop 1
	v_add_f32_dpp v0, v0, v0 quad_perm:[1,0,3,2] row_mask:0xf bank_mask:0xf bound_ctrl:1
	s_nop 1
	v_add_f32_dpp v0, v0, v0 quad_perm:[2,3,0,1] row_mask:0xf bank_mask:0xf bound_ctrl:1
	s_nop 1
	v_add_f32_dpp v0, v0, v0 row_half_mirror row_mask:0xf bank_mask:0xf bound_ctrl:1
	s_nop 1
	v_add_f32_dpp v0, v0, v0 row_mirror row_mask:0xf bank_mask:0xf bound_ctrl:1
	v_fmamk_f32 v0, v0, 0x3c800000, v167
	v_cmp_gt_f32_e32 vcc, s20, v0
	v_mul_f32_e32 v18, 0x4b800000, v0
	s_nop 0
	v_cndmask_b32_e32 v0, v0, v18, vcc
	v_rsq_f32_e32 v0, v0
	s_nop 0
	v_mul_f32_e32 v18, 0x45800000, v0
	v_cndmask_b32_e32 v18, v0, v18, vcc
	ds_read_u16 v0, v74 offset:144
	s_waitcnt lgkmcnt(0)
	v_lshlrev_b32_e32 v22, 16, v0
	ds_read_u16 v0, v75
	s_waitcnt lgkmcnt(0)
	v_lshlrev_b32_e32 v26, 16, v0
	v_lshlrev_b32_e32 v0, 2, v69
	v_lshl_add_u64 v[38:39], s[6:7], 0, v[0:1]
	v_add_co_u32_e32 v38, vcc, s21, v38
	v_sub_f32_e32 v26, v26, v22
	s_nop 0
	v_addc_co_u32_e32 v39, vcc, 0, v39, vcc
	s_waitcnt vmcnt(0)
	v_mov_b32_e32 v30, v126
	v_mov_b32_e32 v69, v1
	s_waitcnt vmcnt(0)
	v_fmac_f32_e32 v22, v30, v26
	v_mul_f32_e32 v26, v36, v18
	v_mov_b32_e32 v36, v120
	v_mov_b32_e32 v38, v121
	s_waitcnt vmcnt(0)
	v_fma_f32 v0, v36, v26, v38
	v_fmac_f32_e32 v0, v43, v22
	v_mul_f32_e32 v0, v6, v0
	v_cvt_pk_bf16_f32 v0, v0, v0
	ds_write_b16 v76, v0 offset:62464
	ds_read_u16 v0, v74 offset:176
	ds_read_u16 v6, v74 offset:208
	s_waitcnt lgkmcnt(1)
	v_lshlrev_b32_e32 v22, 16, v0
	ds_read_u16 v0, v77
	s_waitcnt lgkmcnt(1)
	v_lshlrev_b32_e32 v6, 16, v6
	s_waitcnt lgkmcnt(0)
	v_lshlrev_b32_e32 v26, 16, v0
	v_add_lshl_u32 v0, s37, v73, 2
	v_lshl_add_u64 v[40:41], s[6:7], 0, v[0:1]
	v_add_co_u32_e32 v44, vcc, s21, v40
	v_sub_f32_e32 v26, v26, v22
	s_nop 0
	v_addc_co_u32_e32 v45, vcc, 0, v41, vcc
	v_mov_b32_e32 v39, v127
	s_waitcnt vmcnt(0)
	v_fmac_f32_e32 v22, v39, v26
	v_mul_f32_e32 v26, v37, v18
	v_mov_b32_e32 v37, v122
	v_mov_b32_e32 v40, v123
	v_mov_b32_e32 v41, v128
	s_waitcnt vmcnt(1)
	v_fma_f32 v26, v37, v26, v40
	v_fmac_f32_e32 v26, v43, v22
	v_mul_f32_e32 v10, v10, v26
	v_cvt_pk_bf16_f32 v10, v10, v10
	ds_write_b16 v78, v10 offset:62496
	ds_read_u16 v10, v79
	v_mov_b32_e32 v26, v31
	v_mov_b32_e32 v22, v19
	s_waitcnt lgkmcnt(0)
	v_lshlrev_b32_e32 v10, 16, v10
	v_sub_f32_e32 v10, v10, v6
	s_waitcnt vmcnt(0)
	v_fmac_f32_e32 v6, v41, v10
	v_mul_f32_e32 v10, v35, v18
	v_mov_b32_e32 v42, v138
	v_mov_b32_e32 v35, v139
	v_mul_f32_e32 v18, v34, v18
	s_waitcnt vmcnt(0)
	v_fma_f32 v10, v42, v10, v35
	v_fmac_f32_e32 v10, v43, v6
	v_mul_f32_e32 v6, v14, v10
	v_cvt_pk_bf16_f32 v6, v6, v6
	ds_write_b16 v78, v6 offset:62528
	ds_read_u16 v6, v74 offset:240
	ds_read_u16 v10, v80
	s_waitcnt lgkmcnt(1)
	v_lshlrev_b32_e32 v6, 16, v6
	s_waitcnt lgkmcnt(0)
; __device__ __forceinline__ float bf2f(bf16 v) { return __uint_as_float(((unsigned)v) << 16); }
; __device__ __forceinline__ unsigned f2bf(float f) { return pk2(f, f) & 0xffffu; }
; __device__ __forceinline__ float red16(float v) { v += dpp_mov<0xB1>(v); v += dpp_mov<0x4E>(v); v += dpp_mov<0x141>(v); v += dpp_mov<0x140>(v); return v; }
; __device__ __forceinline__ void rwkv_out_phase(const bf16* Z, const RwkvW w, const bf16* Wl, const float* Ub, const bf16* RHO, const bf16* Y0, const float* BON, bf16* MIX, unsigned char* lds) {
;     ...
;         for (int jj = 0; jj < 4; ++jj) { const int tl = 16 * wave + q4 * 4 + jj; const float bon = BON[(rowbase + tl) * 8 + h];
;             float y[4]; float sum = 0.f;
; #pragma unroll
;             for (int dt = 0; dt < 4; ++dt) { y[dt] = ya[dt][jj] + bf2f(Ys[tl * 72 + 16 * dt + r16]); sum += y[dt]; }
;             const float mean = red16(sum) * (1.f / 64.f); float qq = 0.f;
; #pragma unroll
;             for (int dt = 0; dt < 4; ++dt) { y[dt] -= mean; qq += y[dt] * y[dt]; }
;             const float rstd = rsqrtf(red16(qq) * (1.f / 64.f) + 64e-5f);
; #pragma unroll
;             for (int dt = 0; dt < 4; ++dt) { const int ch = 16 * dt + r16; const float vc = bf2f(Vs[(tl + 1) * 72 + ch]), vp = bf2f(Vs[tl * 72 + ch]);
;                 const float vs = vc + w.mu[1024 + col0 + ch] * (vp - vc);
;                 Ys[tl * 72 + ch] = (bf16)f2bf((y[dt] * rstd * w.ln_g[col0 + ch] + w.ln_b[col0 + ch] + bon * vs) * ga[dt][jj]); } }
	v_lshlrev_b32_e32 v14, 16, v10
	v_mov_b32_e32 v10, v129
	v_sub_f32_e32 v14, v14, v6
	v_lshl_add_u64 v[44:45], s[16:17], 0, v[58:59]
	v_lshlrev_b64 v[44:45], 5, v[44:45]
	v_lshl_add_u64 v[44:45], s[18:19], 0, v[44:45]
	s_waitcnt vmcnt(0)
	v_fmac_f32_e32 v6, v10, v14
	v_mov_b32_e32 v14, v140
	s_nop 0
	v_mov_b32_e32 v0, v141
	s_waitcnt vmcnt(0)
	v_fma_f32 v18, v18, v14, v0
	v_fmac_f32_e32 v18, v43, v6
	v_mul_f32_e32 v2, v2, v18
	v_cvt_pk_bf16_f32 v2, v2, v2
	ds_write_b16 v78, v2 offset:62560
	v_mov_b32_e32 v2, v132
	ds_read_u16 v6, v103 offset:62704
	ds_read_u16 v18, v103 offset:62672
	s_waitcnt lgkmcnt(1)
	v_lshlrev_b32_e32 v44, 16, v6
	s_waitcnt lgkmcnt(0)
	v_lshlrev_b32_e32 v45, 16, v18
	ds_read_u16 v6, v103 offset:62608
	ds_read_u16 v18, v103 offset:62640
	v_pk_add_f32 v[26:27], v[26:27], v[44:45]
	s_waitcnt lgkmcnt(1)
	v_lshlrev_b32_e32 v44, 16, v6
	s_waitcnt lgkmcnt(0)
	v_lshlrev_b32_e32 v45, 16, v18
	v_pk_add_f32 v[18:19], v[22:23], v[44:45]
	s_nop 0
	v_add_f32_e32 v6, 0, v18
	v_add_f32_e32 v6, v6, v19
	v_add_f32_e32 v6, v6, v27
	v_add_f32_e32 v6, v6, v26
	s_nop 1
	v_add_f32_dpp v6, v6, v6 quad_perm:[1,0,3,2] row_mask:0xf bank_mask:0xf bound_ctrl:1
	s_nop 1
	v_add_f32_dpp v6, v6, v6 quad_perm:[2,3,0,1] row_mask:0xf bank_mask:0xf bound_ctrl:1
	s_nop 1
	v_add_f32_dpp v6, v6, v6 row_half_mirror row_mask:0xf bank_mask:0xf bound_ctrl:1
	s_nop 1
	v_add_f32_dpp v6, v6, v6 row_mirror row_mask:0xf bank_mask:0xf bound_ctrl:1
	v_mul_f32_e32 v6, 0x3c800000, v6
	v_pk_add_f32 v[22:23], v[18:19], v[6:7] op_sel_hi:[1,0] neg_lo:[0,1] neg_hi:[0,1]
	v_pk_add_f32 v[18:19], v[26:27], v[6:7] op_sel_hi:[1,0] neg_lo:[0,1] neg_hi:[0,1]
	v_pk_mul_f32 v[44:45], v[22:23], v[22:23]
	v_pk_mul_f32 v[26:27], v[18:19], v[18:19]
	v_add_f32_e32 v6, v44, v45
	v_add_f32_e32 v6, v27, v6
	v_add_f32_e32 v6, v26, v6
	ds_read_u16 v27, v82
	s_waitcnt lgkmcnt(0)
	v_lshlrev_b32_e32 v27, 16, v27
	v_add_f32_dpp v6, v6, v6 quad_perm:[1,0,3,2] row_mask:0xf bank_mask:0xf bound_ctrl:1
	s_nop 1
	v_add_f32_dpp v6, v6, v6 quad_perm:[2,3,0,1] row_mask:0xf bank_mask:0xf bound_ctrl:1
	s_nop 1
	v_add_f32_dpp v6, v6, v6 row_half_mirror row_mask:0xf bank_mask:0xf bound_ctrl:1
	s_nop 1
	v_add_f32_dpp v6, v6, v6 row_mirror row_mask:0xf bank_mask:0xf bound_ctrl:1
	v_fmamk_f32 v6, v6, 0x3c800000, v167
	v_cmp_gt_f32_e32 vcc, s20, v6
	v_mul_f32_e32 v26, 0x4b800000, v6
	s_nop 0
	v_cndmask_b32_e32 v6, v6, v26, vcc
	v_rsq_f32_e32 v6, v6
	s_nop 0
	v_mul_f32_e32 v26, 0x45800000, v6
	v_cndmask_b32_e32 v6, v6, v26, vcc
	ds_read_u16 v26, v81 offset:144
	v_mul_f32_e32 v22, v22, v6
	v_fma_f32 v22, v36, v22, v38
	s_waitcnt lgkmcnt(0)
	v_lshlrev_b32_e32 v26, 16, v26
	v_sub_f32_e32 v27, v27, v26
	v_fmac_f32_e32 v26, v30, v27
	s_waitcnt vmcnt(0)
	v_fmac_f32_e32 v22, v2, v26
	v_mul_f32_e32 v7, v7, v22
	v_cvt_pk_bf16_f32 v7, v7, v7
	ds_write_b16 v83, v7 offset:62464
	ds_read_u16 v7, v81 offset:176
	ds_read_u16 v22, v84
	s_waitcnt lgkmcnt(1)
	v_lshlrev_b32_e32 v7, 16, v7
	s_waitcnt lgkmcnt(0)
	v_lshlrev_b32_e32 v22, 16, v22
	v_sub_f32_e32 v22, v22, v7
	v_fmac_f32_e32 v7, v39, v22
	v_mul_f32_e32 v22, v23, v6
	v_fma_f32 v22, v37, v22, v40
	v_fmac_f32_e32 v22, v2, v7
	v_mul_f32_e32 v7, v11, v22
	v_cvt_pk_bf16_f32 v7, v7, v7
	ds_write_b16 v83, v7 offset:62496
	ds_read_u16 v7, v81 offset:208
	ds_read_u16 v11, v85
	s_waitcnt lgkmcnt(1)
	v_lshlrev_b32_e32 v7, 16, v7
	s_waitcnt lgkmcnt(0)
	v_lshlrev_b32_e32 v11, 16, v11
	v_sub_f32_e32 v11, v11, v7
	v_fmac_f32_e32 v7, v41, v11
	v_mul_f32_e32 v11, v19, v6
	v_fma_f32 v11, v42, v11, v35
	v_fmac_f32_e32 v11, v2, v7
	v_mul_f32_e32 v7, v15, v11
	v_cvt_pk_bf16_f32 v7, v7, v7
	ds_write_b16 v83, v7 offset:62528
	ds_read_u16 v7, v81 offset:240
	ds_read_u16 v11, v86
	v_mul_f32_e32 v6, v18, v6
	v_fma_f32 v6, v14, v6, v0
	v_mov_b32_e32 v18, v20
	s_waitcnt lgkmcnt(1)
	v_lshlrev_b32_e32 v7, 16, v7
	s_waitcnt lgkmcnt(0)
	v_lshlrev_b32_e32 v11, 16, v11
	v_sub_f32_e32 v11, v11, v7
	v_fmac_f32_e32 v7, v10, v11
	v_fmac_f32_e32 v6, v2, v7
	v_mul_f32_e32 v2, v3, v6
	v_cvt_pk_bf16_f32 v2, v2, v2
	ds_write_b16 v83, v2 offset:62560
	v_lshl_add_u64 v[2:3], s[16:17], 0, v[60:61]
	v_lshlrev_b64 v[2:3], 5, v[2:3]
	v_lshl_add_u64 v[2:3], s[18:19], 0, v[2:3]
	v_mov_b32_e32 v11, v133
	ds_read_u16 v2, v104 offset:62560
	ds_read_u16 v3, v104 offset:62528
	v_mov_b32_e32 v6, v32
	v_mov_b32_e32 v7, v28
	v_mov_b32_e32 v19, v24
	s_waitcnt lgkmcnt(1)
	v_lshlrev_b32_e32 v2, 16, v2
	s_waitcnt lgkmcnt(0)
	v_lshlrev_b32_e32 v3, 16, v3
	v_pk_add_f32 v[2:3], v[6:7], v[2:3]
	ds_read_u16 v6, v104 offset:62464
	ds_read_u16 v7, v104 offset:62496
	v_mov_b32_e32 v24, v21
	v_mov_b32_e32 v28, v33
	s_waitcnt lgkmcnt(1)
	v_lshlrev_b32_e32 v6, 16, v6
	s_waitcnt lgkmcnt(0)
	v_lshlrev_b32_e32 v7, 16, v7
	v_pk_add_f32 v[6:7], v[18:19], v[6:7]
	s_nop 0
	v_add_f32_e32 v15, 0, v6
	v_add_f32_e32 v15, v15, v7
	v_add_f32_e32 v15, v15, v3
	v_add_f32_e32 v15, v15, v2
	s_nop 1
	v_add_f32_dpp v15, v15, v15 quad_perm:[1,0,3,2] row_mask:0xf bank_mask:0xf bound_ctrl:1
	s_nop 1
	v_add_f32_dpp v15, v15, v15 quad_perm:[2,3,0,1] row_mask:0xf bank_mask:0xf bound_ctrl:1
	s_nop 1
	v_add_f32_dpp v15, v15, v15 row_half_mirror row_mask:0xf bank_mask:0xf bound_ctrl:1
	s_nop 1
	v_add_f32_dpp v15, v15, v15 row_mirror row_mask:0xf bank_mask:0xf bound_ctrl:1
	v_mul_f32_e32 v18, 0x3c800000, v15
	v_pk_add_f32 v[6:7], v[6:7], v[18:19] op_sel_hi:[1,0] neg_lo:[0,1] neg_hi:[0,1]
	v_pk_add_f32 v[2:3], v[2:3], v[18:19] op_sel_hi:[1,0] neg_lo:[0,1] neg_hi:[0,1]
	v_pk_mul_f32 v[22:23], v[6:7], v[6:7]
	v_pk_mul_f32 v[18:19], v[2:3], v[2:3]
	v_add_f32_e32 v15, v22, v23
	v_add_f32_e32 v15, v19, v15
	v_add_f32_e32 v15, v18, v15
	ds_read_u16 v19, v88
	s_waitcnt lgkmcnt(0)
; __device__ __forceinline__ float bf2f(bf16 v) { return __uint_as_float(((unsigned)v) << 16); }
; __device__ __forceinline__ unsigned f2bf(float f) { return pk2(f, f) & 0xffffu; }
; __device__ __forceinline__ float red16(float v) { v += dpp_mov<0xB1>(v); v += dpp_mov<0x4E>(v); v += dpp_mov<0x141>(v); v += dpp_mov<0x140>(v); return v; }
; __device__ __forceinline__ void rwkv_out_phase(const bf16* Z, const RwkvW w, const bf16* Wl, const float* Ub, const bf16* RHO, const bf16* Y0, const float* BON, bf16* MIX, unsigned char* lds) {
;     ...
;         for (int jj = 0; jj < 4; ++jj) { const int tl = 16 * wave + q4 * 4 + jj; const float bon = BON[(rowbase + tl) * 8 + h];
;             float y[4]; float sum = 0.f;
; #pragma unroll
;             for (int dt = 0; dt < 4; ++dt) { y[dt] = ya[dt][jj] + bf2f(Ys[tl * 72 + 16 * dt + r16]); sum += y[dt]; }
;             const float mean = red16(sum) * (1.f / 64.f); float qq = 0.f;
; #pragma unroll
;             for (int dt = 0; dt < 4; ++dt) { y[dt] -= mean; qq += y[dt] * y[dt]; }
;             const float rstd = rsqrtf(red16(qq) * (1.f / 64.f) + 64e-5f);
; #pragma unroll
;             for (int dt = 0; dt < 4; ++dt) { const int ch = 16 * dt + r16; const float vc = bf2f(Vs[(tl + 1) * 72 + ch]), vp = bf2f(Vs[tl * 72 + ch]);
;                 const float vs = vc + w.mu[1024 + col0 + ch] * (vp - vc);
;                 Ys[tl * 72 + ch] = (bf16)f2bf((y[dt] * rstd * w.ln_g[col0 + ch] + w.ln_b[col0 + ch] + bon * vs) * ga[dt][jj]); } }
; #pragma unroll
;         for (int t2 = 0; t2 < 2; ++t2) { const int cidx = lane + 64 * t2, i = 16 * wave + (cidx >> 3), c8 = (cidx & 7) * 8;
;             *(u32x4*)(MIX + (rowbase + i) * DM + 512 + col0 + c8) = *(const u32x4*)(Ys + i * 72 + c8); }
	v_lshlrev_b32_e32 v19, 16, v19
	v_add_f32_dpp v15, v15, v15 quad_perm:[1,0,3,2] row_mask:0xf bank_mask:0xf bound_ctrl:1
	s_nop 1
	v_add_f32_dpp v15, v15, v15 quad_perm:[2,3,0,1] row_mask:0xf bank_mask:0xf bound_ctrl:1
	s_nop 1
	v_add_f32_dpp v15, v15, v15 row_half_mirror row_mask:0xf bank_mask:0xf bound_ctrl:1
	s_nop 1
	v_add_f32_dpp v15, v15, v15 row_mirror row_mask:0xf bank_mask:0xf bound_ctrl:1
	v_fmamk_f32 v15, v15, 0x3c800000, v167
	v_cmp_gt_f32_e32 vcc, s20, v15
	v_mul_f32_e32 v18, 0x4b800000, v15
	s_nop 0
	v_cndmask_b32_e32 v15, v15, v18, vcc
	v_rsq_f32_e32 v15, v15
	s_nop 0
	v_mul_f32_e32 v18, 0x45800000, v15
	v_cndmask_b32_e32 v15, v15, v18, vcc
	ds_read_u16 v18, v87 offset:144
	v_mul_f32_e32 v6, v6, v15
	v_fma_f32 v6, v36, v6, v38
	v_mul_f32_e32 v7, v7, v15
	v_fma_f32 v7, v37, v7, v40
	s_waitcnt lgkmcnt(0)
	v_lshlrev_b32_e32 v18, 16, v18
	v_sub_f32_e32 v19, v19, v18
	v_fmac_f32_e32 v18, v30, v19
	v_mul_f32_e32 v3, v3, v15
	v_fma_f32 v3, v42, v3, v35
	v_mul_f32_e32 v2, v2, v15
	v_fma_f32 v2, v14, v2, v0
	s_waitcnt vmcnt(0)
	v_fmac_f32_e32 v6, v11, v18
	v_mul_f32_e32 v6, v8, v6
	v_cvt_pk_bf16_f32 v6, v6, v6
	ds_write_b16 v89, v6 offset:62464
	ds_read_u16 v6, v87 offset:176
	ds_read_u16 v8, v87 offset:208
	ds_read_u16 v18, v90
	s_waitcnt lgkmcnt(2)
	v_lshlrev_b32_e32 v6, 16, v6
	s_waitcnt lgkmcnt(0)
	v_lshlrev_b32_e32 v18, 16, v18
	v_sub_f32_e32 v18, v18, v6
	v_fmac_f32_e32 v6, v39, v18
	v_fmac_f32_e32 v7, v11, v6
	v_mul_f32_e32 v6, v12, v7
	v_cvt_pk_bf16_f32 v6, v6, v6
	ds_write_b16 v91, v6 offset:62496
	ds_read_u16 v7, v92
	v_lshlrev_b32_e32 v6, 16, v8
	s_waitcnt lgkmcnt(0)
	v_lshlrev_b32_e32 v7, 16, v7
	v_sub_f32_e32 v7, v7, v6
	v_fmac_f32_e32 v6, v41, v7
	v_fmac_f32_e32 v3, v11, v6
	v_mul_f32_e32 v3, v16, v3
	v_cvt_pk_bf16_f32 v3, v3, v3
	ds_write_b16 v91, v3 offset:62528
	ds_read_u16 v3, v87 offset:240
	ds_read_u16 v6, v93
	s_waitcnt lgkmcnt(1)
	v_lshlrev_b32_e32 v3, 16, v3
	s_waitcnt lgkmcnt(0)
	v_lshlrev_b32_e32 v6, 16, v6
	v_sub_f32_e32 v6, v6, v3
	v_fmac_f32_e32 v3, v10, v6
	v_fmac_f32_e32 v2, v11, v3
	v_mul_f32_e32 v2, v4, v2
	v_cvt_pk_bf16_f32 v2, v2, v2
	ds_write_b16 v91, v2 offset:62560
	v_lshl_add_u64 v[2:3], s[16:17], 0, v[62:63]
	v_lshlrev_b64 v[2:3], 5, v[2:3]
	v_lshl_add_u64 v[2:3], s[18:19], 0, v[2:3]
	v_mov_b32_e32 v4, v134
	ds_read_u16 v2, v104 offset:62704
	ds_read_u16 v3, v104 offset:62672
	ds_read_u16 v6, v104 offset:62608
	ds_read_u16 v7, v104 offset:62640
	ds_read_u16 v12, v95
	s_waitcnt lgkmcnt(4)
	v_lshlrev_b32_e32 v2, 16, v2
	s_waitcnt lgkmcnt(2)
	v_lshlrev_b32_e32 v6, 16, v6
	s_waitcnt lgkmcnt(1)
	v_lshlrev_b32_e32 v7, 16, v7
	v_pk_add_f32 v[6:7], v[24:25], v[6:7]
	v_lshlrev_b32_e32 v3, 16, v3
	v_add_f32_e32 v8, 0, v6
	v_pk_add_f32 v[2:3], v[28:29], v[2:3]
	v_add_f32_e32 v8, v8, v7
	v_add_f32_e32 v8, v8, v3
	v_add_f32_e32 v8, v8, v2
	s_waitcnt lgkmcnt(0)
	v_lshlrev_b32_e32 v12, 16, v12
	v_add_f32_dpp v8, v8, v8 quad_perm:[1,0,3,2] row_mask:0xf bank_mask:0xf bound_ctrl:1
	s_nop 1
	v_add_f32_dpp v8, v8, v8 quad_perm:[2,3,0,1] row_mask:0xf bank_mask:0xf bound_ctrl:1
	s_nop 1
	v_add_f32_dpp v8, v8, v8 row_half_mirror row_mask:0xf bank_mask:0xf bound_ctrl:1
	s_nop 1
	v_add_f32_dpp v8, v8, v8 row_mirror row_mask:0xf bank_mask:0xf bound_ctrl:1
	v_mul_f32_e32 v8, 0x3c800000, v8
	v_pk_add_f32 v[6:7], v[6:7], v[8:9] op_sel_hi:[1,0] neg_lo:[0,1] neg_hi:[0,1]
	v_pk_add_f32 v[2:3], v[2:3], v[8:9] op_sel_hi:[1,0] neg_lo:[0,1] neg_hi:[0,1]
	v_pk_mul_f32 v[18:19], v[6:7], v[6:7]
	v_pk_mul_f32 v[20:21], v[2:3], v[2:3]
	v_add_f32_e32 v8, v18, v19
	v_add_f32_e32 v8, v21, v8
	v_add_f32_e32 v8, v20, v8
	s_nop 1
	v_add_f32_dpp v8, v8, v8 quad_perm:[1,0,3,2] row_mask:0xf bank_mask:0xf bound_ctrl:1
	s_nop 1
	v_add_f32_dpp v8, v8, v8 quad_perm:[2,3,0,1] row_mask:0xf bank_mask:0xf bound_ctrl:1
	s_nop 1
	v_add_f32_dpp v8, v8, v8 row_half_mirror row_mask:0xf bank_mask:0xf bound_ctrl:1
	s_nop 1
	v_add_f32_dpp v8, v8, v8 row_mirror row_mask:0xf bank_mask:0xf bound_ctrl:1
	v_fmamk_f32 v8, v8, 0x3c800000, v167
	v_cmp_gt_f32_e32 vcc, s20, v8
	v_mul_f32_e32 v11, 0x4b800000, v8
	s_nop 0
	v_cndmask_b32_e32 v8, v8, v11, vcc
	v_rsq_f32_e32 v8, v8
	s_nop 0
	v_mul_f32_e32 v11, 0x45800000, v8
	v_cndmask_b32_e32 v8, v8, v11, vcc
	ds_read_u16 v11, v94 offset:144
	v_mul_f32_e32 v6, v6, v8
	v_fmac_f32_e32 v38, v36, v6
	v_mul_f32_e32 v7, v7, v8
	v_fmac_f32_e32 v40, v37, v7
	s_waitcnt lgkmcnt(0)
	v_lshlrev_b32_e32 v11, 16, v11
	v_sub_f32_e32 v12, v12, v11
	v_fmac_f32_e32 v11, v30, v12
	v_mul_f32_e32 v3, v3, v8
	v_fmac_f32_e32 v35, v42, v3
	v_mul_f32_e32 v2, v2, v8
	v_fmac_f32_e32 v0, v14, v2
	s_waitcnt vmcnt(0)
	v_fmac_f32_e32 v38, v4, v11
	v_mul_f32_e32 v6, v9, v38
	v_cvt_pk_bf16_f32 v6, v6, v6
	ds_write_b16 v96, v6 offset:62464
	ds_read_u16 v6, v94 offset:176
	ds_read_u16 v9, v97
	s_waitcnt lgkmcnt(1)
	v_lshlrev_b32_e32 v6, 16, v6
	s_waitcnt lgkmcnt(0)
	v_lshlrev_b32_e32 v9, 16, v9
	v_sub_f32_e32 v9, v9, v6
	v_fmac_f32_e32 v6, v39, v9
	v_fmac_f32_e32 v40, v4, v6
	v_mul_f32_e32 v6, v13, v40
	v_cvt_pk_bf16_f32 v6, v6, v6
	ds_write_b16 v96, v6 offset:62496
	ds_read_u16 v6, v94 offset:208
	ds_read_u16 v7, v98
	s_waitcnt lgkmcnt(1)
	v_lshlrev_b32_e32 v6, 16, v6
	s_waitcnt lgkmcnt(0)
	v_lshlrev_b32_e32 v7, 16, v7
	v_sub_f32_e32 v7, v7, v6
	v_fmac_f32_e32 v6, v41, v7
	v_fmac_f32_e32 v35, v4, v6
	v_mul_f32_e32 v3, v17, v35
	v_cvt_pk_bf16_f32 v3, v3, v3
	ds_write_b16 v96, v3 offset:62528
	ds_read_u16 v3, v94 offset:240
	ds_read_u16 v6, v99
	s_waitcnt lgkmcnt(1)
	v_lshlrev_b32_e32 v3, 16, v3
	s_waitcnt lgkmcnt(0)
	v_lshlrev_b32_e32 v6, 16, v6
	v_sub_f32_e32 v6, v6, v3
	v_fmac_f32_e32 v3, v10, v6
	v_fmac_f32_e32 v0, v4, v3
	v_mul_f32_e32 v0, v5, v0
	v_cvt_pk_bf16_f32 v0, v0, v0
	ds_write_b16 v96, v0 offset:62560
	ds_read_b128 v[2:5], v105 offset:62464
	v_lshl_add_u64 v[6:7], s[16:17], 0, v[56:57]
	v_lshlrev_b64 v[6:7], 11, v[6:7]
	v_lshl_add_u64 v[6:7], s[58:59], 0, v[6:7]
	v_lshl_add_u64 v[6:7], v[6:7], 0, s[60:61]
	v_lshl_add_u64 v[6:7], v[6:7], 0, v[68:69]
	s_waitcnt lgkmcnt(0)
	global_store_dwordx4 v[6:7], v[2:5], off offset:1024
	ds_read_b128 v[2:5], v106 offset:62464
	v_lshl_add_u64 v[6:7], s[16:17], 0, v[64:65]
	v_lshlrev_b64 v[6:7], 11, v[6:7]
	v_lshl_add_u64 v[6:7], s[58:59], 0, v[6:7]
	v_lshl_add_u64 v[6:7], v[6:7], 0, s[60:61]
	v_lshl_add_u64 v[6:7], v[6:7], 0, v[68:69]
	s_waitcnt lgkmcnt(0)
	global_store_dwordx4 v[6:7], v[2:5], off offset:1024
	s_cbranch_scc1 .LBB0_660
